# cv42 + s_nop 0 restored between the M0 write and the LDS-DMA load at the six places where removing the VALU address add had left them adjacent (ISA wait-state rule)
# speedup vs baseline: 1.0173x; 1.0173x over previous
.LBB0_306:
	s_add_u32 s38, s36, 0xfff80080
	s_addc_u32 s39, s37, -1
	s_add_i32 s45, 0, 0x10000
	s_cmp_eq_u32 s27, 28
	s_cselect_b32 s43, s9, s39
	s_cselect_b32 s42, s14, s38
	v_add_u32_e32 v34, s45, v170
	s_cselect_b32 s39, s16, s26
	s_cselect_b32 s38, s17, s25
	s_add_i32 s47, 0, 0x14000
	ds_read_b128 v[160:163], v34
	ds_read_b128 v[164:167], v34 offset:1024
	ds_read_b128 v[174:177], v34 offset:2048
	ds_read_b128 v[184:187], v34 offset:3072
	v_add_u32_e32 v34, s47, v170
	ds_read_b128 v[188:191], v34
	ds_read_b128 v[192:195], v34 offset:1024
	ds_read_b128 v[196:199], v34 offset:2048
	ds_read_b128 v[200:203], v34 offset:3072
	s_add_i32 m0, s35, 0xc000
	ds_read_b128 v[214:217], v173
	ds_read_b128 v[218:221], v173 offset:1024
	ds_read_b128 v[222:225], v173 offset:2048
	ds_read_b128 v[226:229], v173 offset:3072
	ds_read_b128 v[230:233], v173 offset:4096
	ds_read_b128 v[234:237], v173 offset:5120
	ds_read_b128 v[238:241], v173 offset:6144
	ds_read_b128 v[242:245], v173 offset:7168
	global_load_lds_dwordx4 v152, s[36:37]
	s_add_i32 m0, s35, 0xe000
	s_nop 0
	global_load_lds_dwordx4 v156, s[36:37]
	s_waitcnt vmcnt(8)
	s_waitcnt lgkmcnt(0)
	s_barrier
	s_setprio 1
	s_waitcnt lgkmcnt(0)
	v_mfma_f32_16x16x32_bf16 v[132:135], v[160:163], v[214:217], v[132:135]
	v_mfma_f32_16x16x32_bf16 v[128:131], v[174:177], v[214:217], v[128:131]
	v_mfma_f32_16x16x32_bf16 v[116:119], v[160:163], v[222:225], v[116:119]
	v_mfma_f32_16x16x32_bf16 v[112:115], v[174:177], v[222:225], v[112:115]
	v_mfma_f32_16x16x32_bf16 v[100:103], v[160:163], v[230:233], v[100:103]
	v_mfma_f32_16x16x32_bf16 v[96:99], v[174:177], v[230:233], v[96:99]
	v_mfma_f32_16x16x32_bf16 v[84:87], v[160:163], v[238:241], v[84:87]
	v_mfma_f32_16x16x32_bf16 v[80:83], v[174:177], v[238:241], v[80:83]
	v_mfma_f32_16x16x32_bf16 v[132:135], v[164:167], v[218:221], v[132:135]
	v_mfma_f32_16x16x32_bf16 v[128:131], v[184:187], v[218:221], v[128:131]
	v_mfma_f32_16x16x32_bf16 v[116:119], v[164:167], v[226:229], v[116:119]
	v_mfma_f32_16x16x32_bf16 v[112:115], v[184:187], v[226:229], v[112:115]
	v_mfma_f32_16x16x32_bf16 v[100:103], v[164:167], v[234:237], v[100:103]
	v_mfma_f32_16x16x32_bf16 v[96:99], v[184:187], v[234:237], v[96:99]
	v_mfma_f32_16x16x32_bf16 v[84:87], v[164:167], v[242:245], v[84:87]
	v_mfma_f32_16x16x32_bf16 v[80:83], v[184:187], v[242:245], v[80:83]
	s_setprio 0
	s_setprio 1
	v_mfma_f32_16x16x32_bf16 v[124:127], v[188:191], v[214:217], v[124:127]
	v_mfma_f32_16x16x32_bf16 v[120:123], v[196:199], v[214:217], v[120:123]
	v_mfma_f32_16x16x32_bf16 v[108:111], v[188:191], v[222:225], v[108:111]
	v_mfma_f32_16x16x32_bf16 v[104:107], v[196:199], v[222:225], v[104:107]
	v_mfma_f32_16x16x32_bf16 v[92:95], v[188:191], v[230:233], v[92:95]
	v_mfma_f32_16x16x32_bf16 v[88:91], v[196:199], v[230:233], v[88:91]
	v_mfma_f32_16x16x32_bf16 v[76:79], v[188:191], v[238:241], v[76:79]
	v_mfma_f32_16x16x32_bf16 v[72:75], v[196:199], v[238:241], v[72:75]
	v_mfma_f32_16x16x32_bf16 v[124:127], v[192:195], v[218:221], v[124:127]
	v_mfma_f32_16x16x32_bf16 v[120:123], v[200:203], v[218:221], v[120:123]
	v_mfma_f32_16x16x32_bf16 v[108:111], v[192:195], v[226:229], v[108:111]
	v_mfma_f32_16x16x32_bf16 v[104:107], v[200:203], v[226:229], v[104:107]
	v_mfma_f32_16x16x32_bf16 v[92:95], v[192:195], v[234:237], v[92:95]
	v_mfma_f32_16x16x32_bf16 v[88:91], v[200:203], v[234:237], v[88:91]
	v_mfma_f32_16x16x32_bf16 v[76:79], v[192:195], v[242:245], v[76:79]
	v_mfma_f32_16x16x32_bf16 v[72:75], v[200:203], v[242:245], v[72:75]
	s_setprio 0
	s_barrier
	s_add_u32 s98, s38, s22
	s_addc_u32 s99, s39, s23
	s_add_u32 s100, s42, s22
	s_addc_u32 s101, s43, s23
	s_add_i32 s45, s45, s53
	s_mov_b32 m0, s45
	ds_read_b128 v[214:217], v173 offset:16384
	ds_read_b128 v[218:221], v173 offset:17408
	ds_read_b128 v[222:225], v173 offset:18432
	ds_read_b128 v[226:229], v173 offset:19456
	ds_read_b128 v[230:233], v173 offset:20480
	ds_read_b128 v[234:237], v173 offset:21504
	ds_read_b128 v[238:241], v173 offset:22528
	ds_read_b128 v[242:245], v173 offset:23552
	global_load_lds_dwordx4 v136, s[38:39]
	s_add_i32 m0, s45, 0x2000
	s_add_u32 s70, s38, 0x80000
	s_addc_u32 s71, s39, 0
	s_add_i32 s45, s47, s53
	global_load_lds_dwordx4 v140, s[38:39]
	s_mov_b32 m0, s45
	s_nop 0
	global_load_lds_dwordx4 v136, s[70:71]
	s_add_i32 m0, s45, 0x2000
	s_nop 0
	global_load_lds_dwordx4 v140, s[70:71]
	s_mov_b32 m0, s35
	s_nop 0
	global_load_lds_dwordx4 v14, s[42:43]
	s_mov_b32 m0, s54
	s_nop 0
	global_load_lds_dwordx4 v138, s[42:43]
	s_waitcnt vmcnt(8)
	s_waitcnt lgkmcnt(0)
	s_barrier
	s_setprio 1
	s_waitcnt lgkmcnt(0)
	v_mfma_f32_16x16x32_bf16 v[68:71], v[160:163], v[214:217], v[68:71]
	v_mfma_f32_16x16x32_bf16 v[64:67], v[174:177], v[214:217], v[64:67]
	v_mfma_f32_16x16x32_bf16 v[52:55], v[160:163], v[222:225], v[52:55]
	v_mfma_f32_16x16x32_bf16 v[48:51], v[174:177], v[222:225], v[48:51]
	v_mfma_f32_16x16x32_bf16 v[36:39], v[160:163], v[230:233], v[36:39]
	v_mfma_f32_16x16x32_bf16 v[30:33], v[174:177], v[230:233], v[30:33]
	v_mfma_f32_16x16x32_bf16 v[18:21], v[160:163], v[238:241], v[18:21]
	v_mfma_f32_16x16x32_bf16 v[10:13], v[174:177], v[238:241], v[10:13]
	v_mfma_f32_16x16x32_bf16 v[68:71], v[164:167], v[218:221], v[68:71]
	v_mfma_f32_16x16x32_bf16 v[64:67], v[184:187], v[218:221], v[64:67]
	v_mfma_f32_16x16x32_bf16 v[52:55], v[164:167], v[226:229], v[52:55]
	v_mfma_f32_16x16x32_bf16 v[48:51], v[184:187], v[226:229], v[48:51]
	v_mfma_f32_16x16x32_bf16 v[36:39], v[164:167], v[234:237], v[36:39]
	v_mfma_f32_16x16x32_bf16 v[30:33], v[184:187], v[234:237], v[30:33]
	v_mfma_f32_16x16x32_bf16 v[18:21], v[164:167], v[242:245], v[18:21]
	v_mfma_f32_16x16x32_bf16 v[10:13], v[184:187], v[242:245], v[10:13]
	s_setprio 0
	s_setprio 1
	v_mfma_f32_16x16x32_bf16 v[60:63], v[188:191], v[214:217], v[60:63]
	v_mfma_f32_16x16x32_bf16 v[56:59], v[196:199], v[214:217], v[56:59]
	v_mfma_f32_16x16x32_bf16 v[44:47], v[188:191], v[222:225], v[44:47]
	v_mfma_f32_16x16x32_bf16 v[40:43], v[196:199], v[222:225], v[40:43]
	v_mfma_f32_16x16x32_bf16 v[26:29], v[188:191], v[230:233], v[26:29]
	v_mfma_f32_16x16x32_bf16 v[22:25], v[196:199], v[230:233], v[22:25]
	v_mfma_f32_16x16x32_bf16 v[6:9], v[188:191], v[238:241], v[6:9]
	v_mfma_f32_16x16x32_bf16 v[2:5], v[196:199], v[238:241], v[2:5]
	v_mfma_f32_16x16x32_bf16 v[60:63], v[192:195], v[218:221], v[60:63]
	v_mfma_f32_16x16x32_bf16 v[56:59], v[200:203], v[218:221], v[56:59]
	v_mfma_f32_16x16x32_bf16 v[44:47], v[192:195], v[226:229], v[44:47]
	v_mfma_f32_16x16x32_bf16 v[40:43], v[200:203], v[226:229], v[40:43]
	v_mfma_f32_16x16x32_bf16 v[26:29], v[192:195], v[234:237], v[26:29]
	v_mfma_f32_16x16x32_bf16 v[22:25], v[200:203], v[234:237], v[22:25]
	v_mfma_f32_16x16x32_bf16 v[6:9], v[192:195], v[242:245], v[6:9]
	v_mfma_f32_16x16x32_bf16 v[2:5], v[200:203], v[242:245], v[2:5]
	s_setprio 0
	s_barrier
	s_add_i32 s45, 0, 0x18000
	v_add_u32_e32 v34, s45, v170
	s_add_i32 s47, 0, 0x1c000
	ds_read_b128 v[160:163], v34
	ds_read_b128 v[164:167], v34 offset:1024
	ds_read_b128 v[174:177], v34 offset:2048
	ds_read_b128 v[184:187], v34 offset:3072
	v_add_u32_e32 v34, s47, v170
	ds_read_b128 v[188:191], v34
	ds_read_b128 v[192:195], v34 offset:1024
	ds_read_b128 v[196:199], v34 offset:2048
	ds_read_b128 v[200:203], v34 offset:3072
	s_add_u32 s42, s42, 0x80000
	s_addc_u32 s43, s43, 0
	s_mov_b32 m0, s55
	ds_read_b128 v[214:217], v173 offset:32768
	ds_read_b128 v[218:221], v173 offset:33792
	ds_read_b128 v[222:225], v173 offset:34816
	ds_read_b128 v[226:229], v173 offset:35840
	ds_read_b128 v[230:233], v173 offset:36864
	ds_read_b128 v[234:237], v173 offset:37888
	ds_read_b128 v[238:241], v173 offset:38912
	ds_read_b128 v[242:245], v173 offset:39936
	global_load_lds_dwordx4 v14, s[42:43]
	s_mov_b32 m0, s60
	s_nop 0
	global_load_lds_dwordx4 v138, s[42:43]
	s_waitcnt vmcnt(8)
	s_waitcnt lgkmcnt(0)
	s_barrier
	s_setprio 1
	s_waitcnt lgkmcnt(0)
	v_mfma_f32_16x16x32_bf16 v[132:135], v[160:163], v[214:217], v[132:135]
	v_mfma_f32_16x16x32_bf16 v[128:131], v[174:177], v[214:217], v[128:131]
	v_mfma_f32_16x16x32_bf16 v[116:119], v[160:163], v[222:225], v[116:119]
	v_mfma_f32_16x16x32_bf16 v[112:115], v[174:177], v[222:225], v[112:115]
	v_mfma_f32_16x16x32_bf16 v[100:103], v[160:163], v[230:233], v[100:103]
	v_mfma_f32_16x16x32_bf16 v[96:99], v[174:177], v[230:233], v[96:99]
	v_mfma_f32_16x16x32_bf16 v[84:87], v[160:163], v[238:241], v[84:87]
	v_mfma_f32_16x16x32_bf16 v[80:83], v[174:177], v[238:241], v[80:83]
	v_mfma_f32_16x16x32_bf16 v[132:135], v[164:167], v[218:221], v[132:135]
	v_mfma_f32_16x16x32_bf16 v[128:131], v[184:187], v[218:221], v[128:131]
	v_mfma_f32_16x16x32_bf16 v[116:119], v[164:167], v[226:229], v[116:119]
	v_mfma_f32_16x16x32_bf16 v[112:115], v[184:187], v[226:229], v[112:115]
	v_mfma_f32_16x16x32_bf16 v[100:103], v[164:167], v[234:237], v[100:103]
	v_mfma_f32_16x16x32_bf16 v[96:99], v[184:187], v[234:237], v[96:99]
	v_mfma_f32_16x16x32_bf16 v[84:87], v[164:167], v[242:245], v[84:87]
	v_mfma_f32_16x16x32_bf16 v[80:83], v[184:187], v[242:245], v[80:83]
	s_setprio 0
	s_setprio 1
	v_mfma_f32_16x16x32_bf16 v[124:127], v[188:191], v[214:217], v[124:127]
	v_mfma_f32_16x16x32_bf16 v[120:123], v[196:199], v[214:217], v[120:123]
	v_mfma_f32_16x16x32_bf16 v[108:111], v[188:191], v[222:225], v[108:111]
	v_mfma_f32_16x16x32_bf16 v[104:107], v[196:199], v[222:225], v[104:107]
	v_mfma_f32_16x16x32_bf16 v[92:95], v[188:191], v[230:233], v[92:95]
	v_mfma_f32_16x16x32_bf16 v[88:91], v[196:199], v[230:233], v[88:91]
	v_mfma_f32_16x16x32_bf16 v[76:79], v[188:191], v[238:241], v[76:79]
	v_mfma_f32_16x16x32_bf16 v[72:75], v[196:199], v[238:241], v[72:75]
	v_mfma_f32_16x16x32_bf16 v[124:127], v[192:195], v[218:221], v[124:127]
	v_mfma_f32_16x16x32_bf16 v[120:123], v[200:203], v[218:221], v[120:123]
	v_mfma_f32_16x16x32_bf16 v[108:111], v[192:195], v[226:229], v[108:111]
	v_mfma_f32_16x16x32_bf16 v[104:107], v[200:203], v[226:229], v[104:107]
	v_mfma_f32_16x16x32_bf16 v[92:95], v[192:195], v[234:237], v[92:95]
	v_mfma_f32_16x16x32_bf16 v[88:91], v[200:203], v[234:237], v[88:91]
	v_mfma_f32_16x16x32_bf16 v[76:79], v[192:195], v[242:245], v[76:79]
	v_mfma_f32_16x16x32_bf16 v[72:75], v[200:203], v[242:245], v[72:75]
	s_setprio 0
	s_barrier
	s_add_i32 s42, s45, s53
	s_mov_b32 m0, s42
	ds_read_b128 v[214:217], v173 offset:49152
	ds_read_b128 v[218:221], v173 offset:50176
	ds_read_b128 v[222:225], v173 offset:51200
	ds_read_b128 v[226:229], v173 offset:52224
	ds_read_b128 v[230:233], v173 offset:53248
	ds_read_b128 v[234:237], v173 offset:54272
	ds_read_b128 v[238:241], v173 offset:55296
	ds_read_b128 v[242:245], v173 offset:56320
	global_load_lds_dwordx4 v136, s[98:99]
	s_add_i32 m0, s42, 0x2000
	s_add_u32 s38, s38, 0x80080
	s_addc_u32 s39, s39, 0
	s_add_i32 s42, s47, s53
	global_load_lds_dwordx4 v140, s[98:99]
	s_mov_b32 m0, s42
	s_nop 0
	global_load_lds_dwordx4 v136, s[38:39]
	s_add_i32 m0, s42, 0x2000
	s_nop 0
	global_load_lds_dwordx4 v140, s[38:39]
	s_mov_b32 m0, s61
	s_nop 0
	global_load_lds_dwordx4 v14, s[100:101]
	s_mov_b32 m0, s64
	s_nop 0
	global_load_lds_dwordx4 v138, s[100:101]
	s_waitcnt vmcnt(8)
	s_waitcnt lgkmcnt(0)
	s_barrier
	s_setprio 1
	s_waitcnt lgkmcnt(0)
	v_mfma_f32_16x16x32_bf16 v[68:71], v[160:163], v[214:217], v[68:71]
	v_mfma_f32_16x16x32_bf16 v[64:67], v[174:177], v[214:217], v[64:67]
	v_mfma_f32_16x16x32_bf16 v[52:55], v[160:163], v[222:225], v[52:55]
	v_mfma_f32_16x16x32_bf16 v[48:51], v[174:177], v[222:225], v[48:51]
	v_mfma_f32_16x16x32_bf16 v[36:39], v[160:163], v[230:233], v[36:39]
	v_mfma_f32_16x16x32_bf16 v[30:33], v[174:177], v[230:233], v[30:33]
	v_mfma_f32_16x16x32_bf16 v[18:21], v[160:163], v[238:241], v[18:21]
	v_mfma_f32_16x16x32_bf16 v[10:13], v[174:177], v[238:241], v[10:13]
	v_mfma_f32_16x16x32_bf16 v[68:71], v[164:167], v[218:221], v[68:71]
	v_mfma_f32_16x16x32_bf16 v[64:67], v[184:187], v[218:221], v[64:67]
	v_mfma_f32_16x16x32_bf16 v[52:55], v[164:167], v[226:229], v[52:55]
	v_mfma_f32_16x16x32_bf16 v[48:51], v[184:187], v[226:229], v[48:51]
	v_mfma_f32_16x16x32_bf16 v[36:39], v[164:167], v[234:237], v[36:39]
	v_mfma_f32_16x16x32_bf16 v[30:33], v[184:187], v[234:237], v[30:33]
	v_mfma_f32_16x16x32_bf16 v[18:21], v[164:167], v[242:245], v[18:21]
	v_mfma_f32_16x16x32_bf16 v[10:13], v[184:187], v[242:245], v[10:13]
	s_setprio 0
	s_setprio 1
	v_mfma_f32_16x16x32_bf16 v[60:63], v[188:191], v[214:217], v[60:63]
	v_mfma_f32_16x16x32_bf16 v[56:59], v[196:199], v[214:217], v[56:59]
	v_mfma_f32_16x16x32_bf16 v[44:47], v[188:191], v[222:225], v[44:47]
	v_mfma_f32_16x16x32_bf16 v[40:43], v[196:199], v[222:225], v[40:43]
	v_mfma_f32_16x16x32_bf16 v[26:29], v[188:191], v[230:233], v[26:29]
	v_mfma_f32_16x16x32_bf16 v[22:25], v[196:199], v[230:233], v[22:25]
	v_mfma_f32_16x16x32_bf16 v[6:9], v[188:191], v[238:241], v[6:9]
	v_mfma_f32_16x16x32_bf16 v[2:5], v[196:199], v[238:241], v[2:5]
	v_mfma_f32_16x16x32_bf16 v[60:63], v[192:195], v[218:221], v[60:63]
	v_mfma_f32_16x16x32_bf16 v[56:59], v[200:203], v[218:221], v[56:59]
	v_mfma_f32_16x16x32_bf16 v[44:47], v[192:195], v[226:229], v[44:47]
	v_mfma_f32_16x16x32_bf16 v[40:43], v[200:203], v[226:229], v[40:43]
	v_mfma_f32_16x16x32_bf16 v[26:29], v[192:195], v[234:237], v[26:29]
	v_mfma_f32_16x16x32_bf16 v[22:25], v[200:203], v[234:237], v[22:25]
	v_mfma_f32_16x16x32_bf16 v[6:9], v[192:195], v[242:245], v[6:9]
	v_mfma_f32_16x16x32_bf16 v[2:5], v[200:203], v[242:245], v[2:5]
	s_setprio 0
	s_barrier
	s_add_i32 s27, s27, 2
	s_add_u32 s36, s36, 0x100
	s_addc_u32 s37, s37, 0
	s_add_u32 s25, s25, 0x100
	s_addc_u32 s26, s26, 0
	s_cmp_gt_u32 s27, 29
	s_cbranch_scc0 .LBB0_306
	s_and_b64 vcc, exec, s[28:29]
	s_cbranch_vccz .LBB0_309
	s_barrier

.LBB0_1124:
	s_add_i32 vcc_lo, s44, 2
	s_add_u32 s38, s8, 0x100
	s_addc_u32 s39, s9, 0
	s_add_i32 s72, 0, 0x10000
	s_cmp_eq_u32 s29, s44
	s_cselect_b32 s47, s35, s39
	s_cselect_b32 s46, s34, s38
	v_add_u32_e32 v34, s72, v183
	s_cselect_b32 s45, s49, s71
	s_cselect_b32 s44, s48, s70
	s_add_i32 s73, 0, 0x14000
	ds_read_b128 v[42:45], v34
	ds_read_b128 v[46:49], v34 offset:1024
	ds_read_b128 v[74:77], v34 offset:2048
	ds_read_b128 v[78:81], v34 offset:3072
	v_add_u32_e32 v34, s73, v183
	ds_read_b128 v[106:109], v34
	ds_read_b128 v[110:113], v34 offset:1024
	ds_read_b128 v[138:141], v34 offset:2048
	ds_read_b128 v[142:145], v34 offset:3072
	s_add_i32 m0, s25, 0xc000
	ds_read_b128 v[170:173], v205
	ds_read_b128 v[174:177], v205 offset:1024
	ds_read_b128 v[196:199], v205 offset:2048
	ds_read_b128 v[200:203], v205 offset:3072
	ds_read_b128 v[214:217], v205 offset:4096
	ds_read_b128 v[218:221], v205 offset:5120
	ds_read_b128 v[222:225], v205 offset:6144
	ds_read_b128 v[226:229], v205 offset:7168
	global_load_lds_dwordx4 v192, s[8:9]
	s_add_i32 m0, s25, 0xe000
	s_nop 0
	global_load_lds_dwordx4 v194, s[8:9]
	s_waitcnt vmcnt(8)
	s_waitcnt lgkmcnt(0)
	s_barrier
	s_setprio 1
	s_waitcnt lgkmcnt(0)
	v_mfma_f32_16x16x32_bf16 v[62:65], v[42:45], v[170:173], v[62:65]
	v_mfma_f32_16x16x32_bf16 v[58:61], v[74:77], v[170:173], v[58:61]
	v_mfma_f32_16x16x32_bf16 v[94:97], v[42:45], v[196:199], v[94:97]
	v_mfma_f32_16x16x32_bf16 v[90:93], v[74:77], v[196:199], v[90:93]
	v_mfma_f32_16x16x32_bf16 v[118:121], v[42:45], v[214:217], v[118:121]
	v_mfma_f32_16x16x32_bf16 v[114:117], v[74:77], v[214:217], v[114:117]
	v_mfma_f32_16x16x32_bf16 v[134:137], v[42:45], v[222:225], v[134:137]
	v_mfma_f32_16x16x32_bf16 v[130:133], v[74:77], v[222:225], v[130:133]
	v_mfma_f32_16x16x32_bf16 v[62:65], v[46:49], v[174:177], v[62:65]
	v_mfma_f32_16x16x32_bf16 v[58:61], v[78:81], v[174:177], v[58:61]
	v_mfma_f32_16x16x32_bf16 v[94:97], v[46:49], v[200:203], v[94:97]
	v_mfma_f32_16x16x32_bf16 v[90:93], v[78:81], v[200:203], v[90:93]
	v_mfma_f32_16x16x32_bf16 v[118:121], v[46:49], v[218:221], v[118:121]
	v_mfma_f32_16x16x32_bf16 v[114:117], v[78:81], v[218:221], v[114:117]
	v_mfma_f32_16x16x32_bf16 v[134:137], v[46:49], v[226:229], v[134:137]
	v_mfma_f32_16x16x32_bf16 v[130:133], v[78:81], v[226:229], v[130:133]
	s_setprio 0
	s_setprio 1
	v_mfma_f32_16x16x32_bf16 v[166:169], v[106:109], v[170:173], v[166:169]
	v_mfma_f32_16x16x32_bf16 v[162:165], v[138:141], v[170:173], v[162:165]
	v_mfma_f32_16x16x32_bf16 v[158:161], v[106:109], v[196:199], v[158:161]
	v_mfma_f32_16x16x32_bf16 v[154:157], v[138:141], v[196:199], v[154:157]
	v_mfma_f32_16x16x32_bf16 v[150:153], v[106:109], v[214:217], v[150:153]
	v_mfma_f32_16x16x32_bf16 v[146:149], v[138:141], v[214:217], v[146:149]
	v_mfma_f32_16x16x32_bf16 v[126:129], v[106:109], v[222:225], v[126:129]
	v_mfma_f32_16x16x32_bf16 v[122:125], v[138:141], v[222:225], v[122:125]
	v_mfma_f32_16x16x32_bf16 v[166:169], v[110:113], v[174:177], v[166:169]
	v_mfma_f32_16x16x32_bf16 v[162:165], v[142:145], v[174:177], v[162:165]
	v_mfma_f32_16x16x32_bf16 v[158:161], v[110:113], v[200:203], v[158:161]
	v_mfma_f32_16x16x32_bf16 v[154:157], v[142:145], v[200:203], v[154:157]
	v_mfma_f32_16x16x32_bf16 v[150:153], v[110:113], v[218:221], v[150:153]
	v_mfma_f32_16x16x32_bf16 v[146:149], v[142:145], v[218:221], v[146:149]
	v_mfma_f32_16x16x32_bf16 v[126:129], v[110:113], v[226:229], v[126:129]
	v_mfma_f32_16x16x32_bf16 v[122:125], v[142:145], v[226:229], v[122:125]
	s_setprio 0
	s_barrier
	s_add_u32 s98, s44, s22
	s_addc_u32 s99, s45, s23
	s_add_u32 s100, s46, s22
	s_addc_u32 s101, s47, s23
	s_add_i32 s8, s72, s20
	s_mov_b32 m0, s8
	ds_read_b128 v[170:173], v205 offset:16384
	ds_read_b128 v[174:177], v205 offset:17408
	ds_read_b128 v[196:199], v205 offset:18432
	ds_read_b128 v[200:203], v205 offset:19456
	ds_read_b128 v[214:217], v205 offset:20480
	ds_read_b128 v[218:221], v205 offset:21504
	ds_read_b128 v[222:225], v205 offset:22528
	ds_read_b128 v[226:229], v205 offset:23552
	global_load_lds_dwordx4 v184, s[44:45]
	s_add_i32 m0, s8, 0x2000
	s_add_u32 s8, s44, 0xc0000
	s_addc_u32 s9, s45, 0
	s_add_i32 s72, s73, s20
	global_load_lds_dwordx4 v188, s[44:45]
	s_mov_b32 m0, s72
	s_nop 0
	global_load_lds_dwordx4 v184, s[8:9]
	s_add_i32 m0, s72, 0x2000
	s_nop 0
	global_load_lds_dwordx4 v188, s[8:9]
	s_mov_b32 m0, s25
	s_nop 0
	global_load_lds_dwordx4 v14, s[46:47]
	s_mov_b32 m0, s26
	s_nop 0
	global_load_lds_dwordx4 v186, s[46:47]
	s_waitcnt vmcnt(8)
	s_waitcnt lgkmcnt(0)
	s_barrier
	s_setprio 1
	s_waitcnt lgkmcnt(0)
	v_mfma_f32_16x16x32_bf16 v[102:105], v[42:45], v[170:173], v[102:105]
	v_mfma_f32_16x16x32_bf16 v[98:101], v[74:77], v[170:173], v[98:101]
	v_mfma_f32_16x16x32_bf16 v[70:73], v[42:45], v[196:199], v[70:73]
	v_mfma_f32_16x16x32_bf16 v[66:69], v[74:77], v[196:199], v[66:69]
	v_mfma_f32_16x16x32_bf16 v[36:39], v[42:45], v[214:217], v[38:41]
	v_mfma_f32_16x16x32_bf16 v[30:33], v[74:77], v[214:217], v[30:33]
	v_mfma_f32_16x16x32_bf16 v[18:21], v[42:45], v[222:225], v[18:21]
	v_mfma_f32_16x16x32_bf16 v[10:13], v[74:77], v[222:225], v[10:13]
	v_mfma_f32_16x16x32_bf16 v[102:105], v[46:49], v[174:177], v[102:105]
	v_mfma_f32_16x16x32_bf16 v[98:101], v[78:81], v[174:177], v[98:101]
	v_mfma_f32_16x16x32_bf16 v[70:73], v[46:49], v[200:203], v[70:73]
	v_mfma_f32_16x16x32_bf16 v[66:69], v[78:81], v[200:203], v[66:69]
	v_mfma_f32_16x16x32_bf16 v[36:39], v[46:49], v[218:221], v[36:39]
	v_mfma_f32_16x16x32_bf16 v[30:33], v[78:81], v[218:221], v[30:33]
	v_mfma_f32_16x16x32_bf16 v[18:21], v[46:49], v[226:229], v[18:21]
	v_mfma_f32_16x16x32_bf16 v[10:13], v[78:81], v[226:229], v[10:13]
	s_setprio 0
	s_setprio 1
	v_mfma_f32_16x16x32_bf16 v[54:57], v[106:109], v[196:199], v[54:57]
	v_mfma_f32_16x16x32_bf16 v[50:53], v[138:141], v[196:199], v[50:53]
	v_mfma_f32_16x16x32_bf16 v[26:29], v[106:109], v[214:217], v[26:29]
	v_mfma_f32_16x16x32_bf16 v[22:25], v[138:141], v[214:217], v[22:25]
	v_mfma_f32_16x16x32_bf16 v[6:9], v[106:109], v[222:225], v[6:9]
	v_mfma_f32_16x16x32_bf16 v[2:5], v[138:141], v[222:225], v[2:5]
	v_mfma_f32_16x16x32_bf16 v[40:43], v[106:109], v[170:173], v[86:89]
	v_mfma_f32_16x16x32_bf16 v[46:49], v[138:141], v[170:173], v[82:85]
	v_mfma_f32_16x16x32_bf16 v[54:57], v[110:113], v[200:203], v[54:57]
	v_mfma_f32_16x16x32_bf16 v[50:53], v[142:145], v[200:203], v[50:53]
	v_mfma_f32_16x16x32_bf16 v[26:29], v[110:113], v[218:221], v[26:29]
	v_mfma_f32_16x16x32_bf16 v[22:25], v[142:145], v[218:221], v[22:25]
	v_mfma_f32_16x16x32_bf16 v[6:9], v[110:113], v[226:229], v[6:9]
	v_mfma_f32_16x16x32_bf16 v[2:5], v[142:145], v[226:229], v[2:5]
	v_mfma_f32_16x16x32_bf16 v[42:45], v[110:113], v[174:177], v[40:43]
	v_mfma_f32_16x16x32_bf16 v[46:49], v[142:145], v[174:177], v[46:49]
	s_setprio 0
	s_barrier
	s_add_i32 s72, 0, 0x18000
	v_add_u32_e32 v34, s72, v183
	s_add_i32 s73, 0, 0x1c000
	ds_read_b128 v[74:77], v34
	ds_read_b128 v[78:81], v34 offset:1024
	ds_read_b128 v[82:85], v34 offset:2048
	ds_read_b128 v[86:89], v34 offset:3072
	v_add_u32_e32 v34, s73, v183
	ds_read_b128 v[106:109], v34
	ds_read_b128 v[110:113], v34 offset:1024
	ds_read_b128 v[138:141], v34 offset:2048
	ds_read_b128 v[142:145], v34 offset:3072
	s_add_u32 s8, s46, 0xc0000
	s_addc_u32 s9, s47, 0
	s_mov_b32 m0, s27
	ds_read_b128 v[170:173], v205 offset:32768
	ds_read_b128 v[174:177], v205 offset:33792
	ds_read_b128 v[196:199], v205 offset:34816
	ds_read_b128 v[200:203], v205 offset:35840
	ds_read_b128 v[214:217], v205 offset:36864
	ds_read_b128 v[218:221], v205 offset:37888
	ds_read_b128 v[222:225], v205 offset:38912
	ds_read_b128 v[226:229], v205 offset:39936
	global_load_lds_dwordx4 v14, s[8:9]
	s_mov_b32 m0, s31
	s_nop 0
	global_load_lds_dwordx4 v186, s[8:9]
	s_waitcnt vmcnt(8)
	s_waitcnt lgkmcnt(0)
	s_barrier
	s_setprio 1
	s_waitcnt lgkmcnt(0)
	v_mfma_f32_16x16x32_bf16 v[62:65], v[74:77], v[170:173], v[62:65]
	v_mfma_f32_16x16x32_bf16 v[58:61], v[82:85], v[170:173], v[58:61]
	v_mfma_f32_16x16x32_bf16 v[94:97], v[74:77], v[196:199], v[94:97]
	v_mfma_f32_16x16x32_bf16 v[90:93], v[82:85], v[196:199], v[90:93]
	v_mfma_f32_16x16x32_bf16 v[118:121], v[74:77], v[214:217], v[118:121]
	v_mfma_f32_16x16x32_bf16 v[114:117], v[82:85], v[214:217], v[114:117]
	v_mfma_f32_16x16x32_bf16 v[134:137], v[74:77], v[222:225], v[134:137]
	v_mfma_f32_16x16x32_bf16 v[130:133], v[82:85], v[222:225], v[130:133]
	v_mfma_f32_16x16x32_bf16 v[62:65], v[78:81], v[174:177], v[62:65]
	v_mfma_f32_16x16x32_bf16 v[58:61], v[86:89], v[174:177], v[58:61]
	v_mfma_f32_16x16x32_bf16 v[94:97], v[78:81], v[200:203], v[94:97]
	v_mfma_f32_16x16x32_bf16 v[90:93], v[86:89], v[200:203], v[90:93]
	v_mfma_f32_16x16x32_bf16 v[118:121], v[78:81], v[218:221], v[118:121]
	v_mfma_f32_16x16x32_bf16 v[114:117], v[86:89], v[218:221], v[114:117]
	v_mfma_f32_16x16x32_bf16 v[134:137], v[78:81], v[226:229], v[134:137]
	v_mfma_f32_16x16x32_bf16 v[130:133], v[86:89], v[226:229], v[130:133]
	s_setprio 0
	s_setprio 1
	v_mfma_f32_16x16x32_bf16 v[166:169], v[106:109], v[170:173], v[166:169]
	v_mfma_f32_16x16x32_bf16 v[162:165], v[138:141], v[170:173], v[162:165]
	v_mfma_f32_16x16x32_bf16 v[158:161], v[106:109], v[196:199], v[158:161]
	v_mfma_f32_16x16x32_bf16 v[154:157], v[138:141], v[196:199], v[154:157]
	v_mfma_f32_16x16x32_bf16 v[150:153], v[106:109], v[214:217], v[150:153]
	v_mfma_f32_16x16x32_bf16 v[146:149], v[138:141], v[214:217], v[146:149]
	v_mfma_f32_16x16x32_bf16 v[126:129], v[106:109], v[222:225], v[126:129]
	v_mfma_f32_16x16x32_bf16 v[122:125], v[138:141], v[222:225], v[122:125]
	v_mfma_f32_16x16x32_bf16 v[166:169], v[110:113], v[174:177], v[166:169]
	v_mfma_f32_16x16x32_bf16 v[162:165], v[142:145], v[174:177], v[162:165]
	v_mfma_f32_16x16x32_bf16 v[158:161], v[110:113], v[200:203], v[158:161]
	v_mfma_f32_16x16x32_bf16 v[154:157], v[142:145], v[200:203], v[154:157]
	v_mfma_f32_16x16x32_bf16 v[150:153], v[110:113], v[218:221], v[150:153]
	v_mfma_f32_16x16x32_bf16 v[146:149], v[142:145], v[218:221], v[146:149]
	v_mfma_f32_16x16x32_bf16 v[126:129], v[110:113], v[226:229], v[126:129]
	v_mfma_f32_16x16x32_bf16 v[122:125], v[142:145], v[226:229], v[122:125]
	s_setprio 0
	s_barrier
	s_add_i32 s8, s72, s20
	s_mov_b32 m0, s8
	ds_read_b128 v[170:173], v205 offset:49152
	ds_read_b128 v[174:177], v205 offset:50176
	ds_read_b128 v[196:199], v205 offset:51200
	ds_read_b128 v[200:203], v205 offset:52224
	ds_read_b128 v[214:217], v205 offset:53248
	ds_read_b128 v[218:221], v205 offset:54272
	ds_read_b128 v[222:225], v205 offset:55296
	ds_read_b128 v[226:229], v205 offset:56320
	global_load_lds_dwordx4 v184, s[98:99]
	s_add_i32 m0, s8, 0x2000
	s_add_u32 s8, s44, 0xc0080
	s_addc_u32 s9, s45, 0
	s_add_i32 s44, s73, s20
	global_load_lds_dwordx4 v188, s[98:99]
	s_mov_b32 m0, s44
	s_nop 0
	global_load_lds_dwordx4 v184, s[8:9]
	s_add_i32 m0, s44, 0x2000
	s_nop 0
	global_load_lds_dwordx4 v188, s[8:9]
	s_mov_b32 m0, s52
	s_nop 0
	global_load_lds_dwordx4 v14, s[100:101]
	s_mov_b32 m0, s53
	s_nop 0
	global_load_lds_dwordx4 v186, s[100:101]
	s_waitcnt vmcnt(8)
	s_waitcnt lgkmcnt(0)
	s_barrier
	s_setprio 1
	s_waitcnt lgkmcnt(0)
	v_mfma_f32_16x16x32_bf16 v[102:105], v[74:77], v[170:173], v[102:105]
	v_mfma_f32_16x16x32_bf16 v[98:101], v[82:85], v[170:173], v[98:101]
	v_mfma_f32_16x16x32_bf16 v[70:73], v[74:77], v[196:199], v[70:73]
	v_mfma_f32_16x16x32_bf16 v[66:69], v[82:85], v[196:199], v[66:69]
	v_mfma_f32_16x16x32_bf16 v[36:39], v[74:77], v[214:217], v[36:39]
	v_mfma_f32_16x16x32_bf16 v[30:33], v[82:85], v[214:217], v[30:33]
	v_mfma_f32_16x16x32_bf16 v[18:21], v[74:77], v[222:225], v[18:21]
	v_mfma_f32_16x16x32_bf16 v[10:13], v[82:85], v[222:225], v[10:13]
	v_mfma_f32_16x16x32_bf16 v[102:105], v[78:81], v[174:177], v[102:105]
	v_mfma_f32_16x16x32_bf16 v[98:101], v[86:89], v[174:177], v[98:101]
	v_mfma_f32_16x16x32_bf16 v[70:73], v[78:81], v[200:203], v[70:73]
	v_mfma_f32_16x16x32_bf16 v[66:69], v[86:89], v[200:203], v[66:69]
	v_mfma_f32_16x16x32_bf16 v[38:41], v[78:81], v[218:221], v[36:39]
	v_mfma_f32_16x16x32_bf16 v[30:33], v[86:89], v[218:221], v[30:33]
	v_mfma_f32_16x16x32_bf16 v[18:21], v[78:81], v[226:229], v[18:21]
	v_mfma_f32_16x16x32_bf16 v[10:13], v[86:89], v[226:229], v[10:13]
	s_setprio 0
	s_setprio 1
	v_mfma_f32_16x16x32_bf16 v[42:45], v[106:109], v[170:173], v[42:45]
	v_mfma_f32_16x16x32_bf16 v[86:89], v[110:113], v[174:177], v[42:45]
	v_mfma_f32_16x16x32_bf16 v[42:45], v[138:141], v[170:173], v[46:49]
	v_mfma_f32_16x16x32_bf16 v[82:85], v[142:145], v[174:177], v[42:45]
	v_mfma_f32_16x16x32_bf16 v[42:45], v[106:109], v[196:199], v[54:57]
	v_mfma_f32_16x16x32_bf16 v[54:57], v[110:113], v[200:203], v[42:45]
	v_mfma_f32_16x16x32_bf16 v[42:45], v[138:141], v[196:199], v[50:53]
	v_mfma_f32_16x16x32_bf16 v[26:29], v[106:109], v[214:217], v[26:29]
	v_mfma_f32_16x16x32_bf16 v[22:25], v[138:141], v[214:217], v[22:25]
	v_mfma_f32_16x16x32_bf16 v[6:9], v[106:109], v[222:225], v[6:9]
	v_mfma_f32_16x16x32_bf16 v[2:5], v[138:141], v[222:225], v[2:5]
	v_mfma_f32_16x16x32_bf16 v[50:53], v[142:145], v[200:203], v[42:45]
	v_mfma_f32_16x16x32_bf16 v[26:29], v[110:113], v[218:221], v[26:29]
	v_mfma_f32_16x16x32_bf16 v[22:25], v[142:145], v[218:221], v[22:25]
	v_mfma_f32_16x16x32_bf16 v[6:9], v[110:113], v[226:229], v[6:9]
	v_mfma_f32_16x16x32_bf16 v[2:5], v[142:145], v[226:229], v[2:5]
	s_setprio 0
	s_barrier
	s_add_u32 s70, s70, 0x100
	s_addc_u32 s71, s71, 0
	s_cmp_ge_i32 vcc_lo, s51
	s_mov_b64 s[8:9], s[38:39]
	s_mov_b32 s44, vcc_lo
	s_cbranch_scc0 .LBB0_1124
	s_and_b64 vcc, exec, s[12:13]
	s_cbranch_vccz .LBB0_1127
	s_barrier

.LBB0_1508:
	s_add_i32 s39, s35, 2
	s_add_u32 s50, s48, 0xfff80080
	s_addc_u32 s51, s49, -1
	s_add_i32 s72, 0, 0x10000
	s_cmp_eq_u32 s9, s35
	s_cselect_b32 s53, s37, s51
	s_cselect_b32 s52, s36, s50
	s_cselect_b32 s51, s45, s29
	s_cselect_b32 s50, s44, s13
	s_add_i32 s35, 0, 0x14000
	v_add_u32_e32 v160, s72, v152
	v_add_u32_e32 v176, s35, v152
	ds_read_b128 v[136:139], v160
	ds_read_b128 v[148:151], v160 offset:1024
	ds_read_b128 v[156:159], v160 offset:2048
	ds_read_b128 v[160:163], v160 offset:3072
	ds_read_b128 v[164:167], v176
	ds_read_b128 v[168:171], v176 offset:1024
	ds_read_b128 v[172:175], v176 offset:2048
	ds_read_b128 v[184:187], v176 offset:3072
	s_add_i32 m0, s25, 0xc000
	ds_read_b128 v[188:191], v155
	ds_read_b128 v[192:195], v155 offset:1024
	ds_read_b128 v[196:199], v155 offset:2048
	ds_read_b128 v[200:203], v155 offset:3072
	ds_read_b128 v[214:217], v155 offset:4096
	ds_read_b128 v[218:221], v155 offset:5120
	ds_read_b128 v[222:225], v155 offset:6144
	ds_read_b128 v[226:229], v155 offset:7168
	global_load_lds_dwordx4 v144, s[48:49]
	s_add_i32 m0, s25, 0xe000
	s_nop 0
	global_load_lds_dwordx4 v146, s[48:49]
	s_waitcnt vmcnt(8)
	s_waitcnt lgkmcnt(0)
	s_barrier
	s_setprio 1
	s_waitcnt lgkmcnt(0)
	v_mfma_f32_16x16x32_bf16 v[132:135], v[136:139], v[188:191], v[132:135]
	v_mfma_f32_16x16x32_bf16 v[128:131], v[156:159], v[188:191], v[128:131]
	v_mfma_f32_16x16x32_bf16 v[116:119], v[136:139], v[196:199], v[116:119]
	v_mfma_f32_16x16x32_bf16 v[112:115], v[156:159], v[196:199], v[112:115]
	v_mfma_f32_16x16x32_bf16 v[100:103], v[136:139], v[214:217], v[100:103]
	v_mfma_f32_16x16x32_bf16 v[96:99], v[156:159], v[214:217], v[96:99]
	v_mfma_f32_16x16x32_bf16 v[84:87], v[136:139], v[222:225], v[84:87]
	v_mfma_f32_16x16x32_bf16 v[80:83], v[156:159], v[222:225], v[80:83]
	v_mfma_f32_16x16x32_bf16 v[132:135], v[148:151], v[192:195], v[132:135]
	v_mfma_f32_16x16x32_bf16 v[128:131], v[160:163], v[192:195], v[128:131]
	v_mfma_f32_16x16x32_bf16 v[116:119], v[148:151], v[200:203], v[116:119]
	v_mfma_f32_16x16x32_bf16 v[112:115], v[160:163], v[200:203], v[112:115]
	v_mfma_f32_16x16x32_bf16 v[100:103], v[148:151], v[218:221], v[100:103]
	v_mfma_f32_16x16x32_bf16 v[96:99], v[160:163], v[218:221], v[96:99]
	v_mfma_f32_16x16x32_bf16 v[84:87], v[148:151], v[226:229], v[84:87]
	v_mfma_f32_16x16x32_bf16 v[80:83], v[160:163], v[226:229], v[80:83]
	s_setprio 0
	s_setprio 1
	v_mfma_f32_16x16x32_bf16 v[124:127], v[164:167], v[188:191], v[124:127]
	v_mfma_f32_16x16x32_bf16 v[120:123], v[172:175], v[188:191], v[120:123]
	v_mfma_f32_16x16x32_bf16 v[108:111], v[164:167], v[196:199], v[108:111]
	v_mfma_f32_16x16x32_bf16 v[104:107], v[172:175], v[196:199], v[104:107]
	v_mfma_f32_16x16x32_bf16 v[92:95], v[164:167], v[214:217], v[92:95]
	v_mfma_f32_16x16x32_bf16 v[88:91], v[172:175], v[214:217], v[88:91]
	v_mfma_f32_16x16x32_bf16 v[76:79], v[164:167], v[222:225], v[76:79]
	v_mfma_f32_16x16x32_bf16 v[72:75], v[172:175], v[222:225], v[72:75]
	v_mfma_f32_16x16x32_bf16 v[124:127], v[168:171], v[192:195], v[124:127]
	v_mfma_f32_16x16x32_bf16 v[120:123], v[184:187], v[192:195], v[120:123]
	v_mfma_f32_16x16x32_bf16 v[108:111], v[168:171], v[200:203], v[108:111]
	v_mfma_f32_16x16x32_bf16 v[104:107], v[184:187], v[200:203], v[104:107]
	v_mfma_f32_16x16x32_bf16 v[92:95], v[168:171], v[218:221], v[92:95]
	v_mfma_f32_16x16x32_bf16 v[88:91], v[184:187], v[218:221], v[88:91]
	v_mfma_f32_16x16x32_bf16 v[76:79], v[168:171], v[226:229], v[76:79]
	v_mfma_f32_16x16x32_bf16 v[72:75], v[184:187], v[226:229], v[72:75]
	s_setprio 0
	s_barrier
	s_add_u32 s98, s50, s22
	s_addc_u32 s99, s51, s23
	s_add_u32 s100, s52, s22
	s_addc_u32 s101, s53, s23
	s_add_i32 s72, s72, s20
	s_mov_b32 m0, s72
	ds_read_b128 v[188:191], v155 offset:16384
	ds_read_b128 v[192:195], v155 offset:17408
	ds_read_b128 v[196:199], v155 offset:18432
	ds_read_b128 v[200:203], v155 offset:19456
	ds_read_b128 v[214:217], v155 offset:20480
	ds_read_b128 v[218:221], v155 offset:21504
	ds_read_b128 v[222:225], v155 offset:22528
	ds_read_b128 v[226:229], v155 offset:23552
	global_load_lds_dwordx4 v34, s[50:51]
	s_add_i32 m0, s72, 0x2000
	s_add_u32 s72, s50, 0x80000
	s_addc_u32 s73, s51, 0
	s_add_i32 s35, s35, s20
	global_load_lds_dwordx4 v142, s[50:51]
	s_mov_b32 m0, s35
	s_nop 0
	global_load_lds_dwordx4 v34, s[72:73]
	s_add_i32 m0, s35, 0x2000
	s_nop 0
	global_load_lds_dwordx4 v142, s[72:73]
	s_mov_b32 m0, s25
	s_nop 0
	global_load_lds_dwordx4 v14, s[52:53]
	s_mov_b32 m0, s26
	s_nop 0
	global_load_lds_dwordx4 v140, s[52:53]
	s_waitcnt vmcnt(8)
	s_waitcnt lgkmcnt(0)
	s_barrier
	s_setprio 1
	s_waitcnt lgkmcnt(0)
	v_mfma_f32_16x16x32_bf16 v[68:71], v[136:139], v[188:191], v[68:71]
	v_mfma_f32_16x16x32_bf16 v[64:67], v[156:159], v[188:191], v[64:67]
	v_mfma_f32_16x16x32_bf16 v[52:55], v[136:139], v[196:199], v[52:55]
	v_mfma_f32_16x16x32_bf16 v[48:51], v[156:159], v[196:199], v[48:51]
	v_mfma_f32_16x16x32_bf16 v[36:39], v[136:139], v[214:217], v[36:39]
	v_mfma_f32_16x16x32_bf16 v[30:33], v[156:159], v[214:217], v[30:33]
	v_mfma_f32_16x16x32_bf16 v[18:21], v[136:139], v[222:225], v[18:21]
	v_mfma_f32_16x16x32_bf16 v[10:13], v[156:159], v[222:225], v[10:13]
	v_mfma_f32_16x16x32_bf16 v[68:71], v[148:151], v[192:195], v[68:71]
	v_mfma_f32_16x16x32_bf16 v[64:67], v[160:163], v[192:195], v[64:67]
	v_mfma_f32_16x16x32_bf16 v[52:55], v[148:151], v[200:203], v[52:55]
	v_mfma_f32_16x16x32_bf16 v[48:51], v[160:163], v[200:203], v[48:51]
	v_mfma_f32_16x16x32_bf16 v[36:39], v[148:151], v[218:221], v[36:39]
	v_mfma_f32_16x16x32_bf16 v[30:33], v[160:163], v[218:221], v[30:33]
	v_mfma_f32_16x16x32_bf16 v[18:21], v[148:151], v[226:229], v[18:21]
	v_mfma_f32_16x16x32_bf16 v[10:13], v[160:163], v[226:229], v[10:13]
	s_setprio 0
	s_setprio 1
	v_mfma_f32_16x16x32_bf16 v[60:63], v[164:167], v[188:191], v[60:63]
	v_mfma_f32_16x16x32_bf16 v[56:59], v[172:175], v[188:191], v[56:59]
	v_mfma_f32_16x16x32_bf16 v[44:47], v[164:167], v[196:199], v[44:47]
	v_mfma_f32_16x16x32_bf16 v[40:43], v[172:175], v[196:199], v[40:43]
	v_mfma_f32_16x16x32_bf16 v[26:29], v[164:167], v[214:217], v[26:29]
	v_mfma_f32_16x16x32_bf16 v[22:25], v[172:175], v[214:217], v[22:25]
	v_mfma_f32_16x16x32_bf16 v[6:9], v[164:167], v[222:225], v[6:9]
	v_mfma_f32_16x16x32_bf16 v[2:5], v[172:175], v[222:225], v[2:5]
	v_mfma_f32_16x16x32_bf16 v[60:63], v[168:171], v[192:195], v[60:63]
	v_mfma_f32_16x16x32_bf16 v[56:59], v[184:187], v[192:195], v[56:59]
	v_mfma_f32_16x16x32_bf16 v[44:47], v[168:171], v[200:203], v[44:47]
	v_mfma_f32_16x16x32_bf16 v[40:43], v[184:187], v[200:203], v[40:43]
	v_mfma_f32_16x16x32_bf16 v[26:29], v[168:171], v[218:221], v[26:29]
	v_mfma_f32_16x16x32_bf16 v[22:25], v[184:187], v[218:221], v[22:25]
	v_mfma_f32_16x16x32_bf16 v[6:9], v[168:171], v[226:229], v[6:9]
	v_mfma_f32_16x16x32_bf16 v[2:5], v[184:187], v[226:229], v[2:5]
	s_setprio 0
	s_barrier
	s_add_i32 s35, 0, 0x18000
	s_add_i32 s72, 0, 0x1c000
	v_add_u32_e32 v160, s35, v152
	v_add_u32_e32 v183, s72, v152
	ds_read_b128 v[136:139], v160
	ds_read_b128 v[148:151], v160 offset:1024
	ds_read_b128 v[156:159], v160 offset:2048
	ds_read_b128 v[160:163], v160 offset:3072
	ds_read_b128 v[164:167], v183
	ds_read_b128 v[168:171], v183 offset:1024
	ds_read_b128 v[172:175], v183 offset:2048
	ds_read_b128 v[184:187], v183 offset:3072
	s_add_u32 s52, s52, 0x80000
	s_addc_u32 s53, s53, 0
	s_mov_b32 m0, s27
	ds_read_b128 v[188:191], v155 offset:32768
	ds_read_b128 v[192:195], v155 offset:33792
	ds_read_b128 v[196:199], v155 offset:34816
	ds_read_b128 v[200:203], v155 offset:35840
	ds_read_b128 v[214:217], v155 offset:36864
	ds_read_b128 v[218:221], v155 offset:37888
	ds_read_b128 v[222:225], v155 offset:38912
	ds_read_b128 v[226:229], v155 offset:39936
	global_load_lds_dwordx4 v14, s[52:53]
	s_mov_b32 m0, s31
	s_nop 0
	global_load_lds_dwordx4 v140, s[52:53]
	s_waitcnt vmcnt(8)
	s_waitcnt lgkmcnt(0)
	s_barrier
	s_setprio 1
	s_waitcnt lgkmcnt(0)
	v_mfma_f32_16x16x32_bf16 v[132:135], v[136:139], v[188:191], v[132:135]
	v_mfma_f32_16x16x32_bf16 v[128:131], v[156:159], v[188:191], v[128:131]
	v_mfma_f32_16x16x32_bf16 v[116:119], v[136:139], v[196:199], v[116:119]
	v_mfma_f32_16x16x32_bf16 v[112:115], v[156:159], v[196:199], v[112:115]
	v_mfma_f32_16x16x32_bf16 v[100:103], v[136:139], v[214:217], v[100:103]
	v_mfma_f32_16x16x32_bf16 v[96:99], v[156:159], v[214:217], v[96:99]
	v_mfma_f32_16x16x32_bf16 v[84:87], v[136:139], v[222:225], v[84:87]
	v_mfma_f32_16x16x32_bf16 v[80:83], v[156:159], v[222:225], v[80:83]
	v_mfma_f32_16x16x32_bf16 v[132:135], v[148:151], v[192:195], v[132:135]
	v_mfma_f32_16x16x32_bf16 v[128:131], v[160:163], v[192:195], v[128:131]
	v_mfma_f32_16x16x32_bf16 v[116:119], v[148:151], v[200:203], v[116:119]
	v_mfma_f32_16x16x32_bf16 v[112:115], v[160:163], v[200:203], v[112:115]
	v_mfma_f32_16x16x32_bf16 v[100:103], v[148:151], v[218:221], v[100:103]
	v_mfma_f32_16x16x32_bf16 v[96:99], v[160:163], v[218:221], v[96:99]
	v_mfma_f32_16x16x32_bf16 v[84:87], v[148:151], v[226:229], v[84:87]
	v_mfma_f32_16x16x32_bf16 v[80:83], v[160:163], v[226:229], v[80:83]
	s_setprio 0
	s_setprio 1
	v_mfma_f32_16x16x32_bf16 v[124:127], v[164:167], v[188:191], v[124:127]
	v_mfma_f32_16x16x32_bf16 v[120:123], v[172:175], v[188:191], v[120:123]
	v_mfma_f32_16x16x32_bf16 v[108:111], v[164:167], v[196:199], v[108:111]
	v_mfma_f32_16x16x32_bf16 v[104:107], v[172:175], v[196:199], v[104:107]
	v_mfma_f32_16x16x32_bf16 v[92:95], v[164:167], v[214:217], v[92:95]
	v_mfma_f32_16x16x32_bf16 v[88:91], v[172:175], v[214:217], v[88:91]
	v_mfma_f32_16x16x32_bf16 v[76:79], v[164:167], v[222:225], v[76:79]
	v_mfma_f32_16x16x32_bf16 v[72:75], v[172:175], v[222:225], v[72:75]
	v_mfma_f32_16x16x32_bf16 v[124:127], v[168:171], v[192:195], v[124:127]
	v_mfma_f32_16x16x32_bf16 v[120:123], v[184:187], v[192:195], v[120:123]
	v_mfma_f32_16x16x32_bf16 v[108:111], v[168:171], v[200:203], v[108:111]
	v_mfma_f32_16x16x32_bf16 v[104:107], v[184:187], v[200:203], v[104:107]
	v_mfma_f32_16x16x32_bf16 v[92:95], v[168:171], v[218:221], v[92:95]
	v_mfma_f32_16x16x32_bf16 v[88:91], v[184:187], v[218:221], v[88:91]
	v_mfma_f32_16x16x32_bf16 v[76:79], v[168:171], v[226:229], v[76:79]
	v_mfma_f32_16x16x32_bf16 v[72:75], v[184:187], v[226:229], v[72:75]
	s_setprio 0
	s_barrier
	s_add_i32 s35, s35, s20
	s_mov_b32 m0, s35
	ds_read_b128 v[188:191], v155 offset:49152
	ds_read_b128 v[192:195], v155 offset:50176
	ds_read_b128 v[196:199], v155 offset:51200
	ds_read_b128 v[200:203], v155 offset:52224
	ds_read_b128 v[214:217], v155 offset:53248
	ds_read_b128 v[218:221], v155 offset:54272
	ds_read_b128 v[222:225], v155 offset:55296
	ds_read_b128 v[226:229], v155 offset:56320
	global_load_lds_dwordx4 v34, s[98:99]
	s_add_i32 m0, s35, 0x2000
	s_add_u32 s50, s50, 0x80080
	s_addc_u32 s51, s51, 0
	s_add_i32 s35, s72, s20
	global_load_lds_dwordx4 v142, s[98:99]
	s_mov_b32 m0, s35
	s_nop 0
	global_load_lds_dwordx4 v34, s[50:51]
	s_add_i32 m0, s35, 0x2000
	s_nop 0
	global_load_lds_dwordx4 v142, s[50:51]
	s_mov_b32 m0, s60
	s_nop 0
	global_load_lds_dwordx4 v14, s[100:101]
	s_mov_b32 m0, s61
	s_nop 0
	global_load_lds_dwordx4 v140, s[100:101]
	s_waitcnt vmcnt(8)
	s_waitcnt lgkmcnt(0)
	s_barrier
	s_setprio 1
	s_waitcnt lgkmcnt(0)
	v_mfma_f32_16x16x32_bf16 v[68:71], v[136:139], v[188:191], v[68:71]
	v_mfma_f32_16x16x32_bf16 v[64:67], v[156:159], v[188:191], v[64:67]
	v_mfma_f32_16x16x32_bf16 v[52:55], v[136:139], v[196:199], v[52:55]
	v_mfma_f32_16x16x32_bf16 v[48:51], v[156:159], v[196:199], v[48:51]
	v_mfma_f32_16x16x32_bf16 v[36:39], v[136:139], v[214:217], v[36:39]
	v_mfma_f32_16x16x32_bf16 v[30:33], v[156:159], v[214:217], v[30:33]
	v_mfma_f32_16x16x32_bf16 v[18:21], v[136:139], v[222:225], v[18:21]
	v_mfma_f32_16x16x32_bf16 v[10:13], v[156:159], v[222:225], v[10:13]
	v_mfma_f32_16x16x32_bf16 v[68:71], v[148:151], v[192:195], v[68:71]
	v_mfma_f32_16x16x32_bf16 v[64:67], v[160:163], v[192:195], v[64:67]
	v_mfma_f32_16x16x32_bf16 v[52:55], v[148:151], v[200:203], v[52:55]
	v_mfma_f32_16x16x32_bf16 v[48:51], v[160:163], v[200:203], v[48:51]
	v_mfma_f32_16x16x32_bf16 v[36:39], v[148:151], v[218:221], v[36:39]
	v_mfma_f32_16x16x32_bf16 v[30:33], v[160:163], v[218:221], v[30:33]
	v_mfma_f32_16x16x32_bf16 v[18:21], v[148:151], v[226:229], v[18:21]
	v_mfma_f32_16x16x32_bf16 v[10:13], v[160:163], v[226:229], v[10:13]
	s_setprio 0
	s_setprio 1
	v_mfma_f32_16x16x32_bf16 v[60:63], v[164:167], v[188:191], v[60:63]
	v_mfma_f32_16x16x32_bf16 v[56:59], v[172:175], v[188:191], v[56:59]
	v_mfma_f32_16x16x32_bf16 v[44:47], v[164:167], v[196:199], v[44:47]
	v_mfma_f32_16x16x32_bf16 v[40:43], v[172:175], v[196:199], v[40:43]
	v_mfma_f32_16x16x32_bf16 v[26:29], v[164:167], v[214:217], v[26:29]
	v_mfma_f32_16x16x32_bf16 v[22:25], v[172:175], v[214:217], v[22:25]
	v_mfma_f32_16x16x32_bf16 v[6:9], v[164:167], v[222:225], v[6:9]
	v_mfma_f32_16x16x32_bf16 v[2:5], v[172:175], v[222:225], v[2:5]
	v_mfma_f32_16x16x32_bf16 v[60:63], v[168:171], v[192:195], v[60:63]
	v_mfma_f32_16x16x32_bf16 v[56:59], v[184:187], v[192:195], v[56:59]
	v_mfma_f32_16x16x32_bf16 v[44:47], v[168:171], v[200:203], v[44:47]
	v_mfma_f32_16x16x32_bf16 v[40:43], v[184:187], v[200:203], v[40:43]
	v_mfma_f32_16x16x32_bf16 v[26:29], v[168:171], v[218:221], v[26:29]
	v_mfma_f32_16x16x32_bf16 v[22:25], v[184:187], v[218:221], v[22:25]
	v_mfma_f32_16x16x32_bf16 v[6:9], v[168:171], v[226:229], v[6:9]
	v_mfma_f32_16x16x32_bf16 v[2:5], v[184:187], v[226:229], v[2:5]
	s_setprio 0
	s_barrier
	s_add_u32 s48, s48, 0x100
	s_addc_u32 s49, s49, 0
	s_add_u32 s13, s13, 0x100
	s_addc_u32 s29, s29, 0
	s_cmp_ge_i32 s39, s71
	s_mov_b32 s35, s39
	s_cbranch_scc0 .LBB0_1508
	s_and_b64 vcc, exec, s[10:11]
	s_cbranch_vccz .LBB0_1511

.LBB0_1664:
	s_add_u32 s44, s42, 0xfff80080
	s_addc_u32 s45, s43, -1
	s_add_i32 s64, 0, 0x10000
	s_cmp_eq_u32 s61, 28
	s_cselect_b32 s47, s29, s45
	s_cselect_b32 s46, s53, s44
	v_add_u32_e32 v151, s64, v141
	s_cselect_b32 s45, s13, s60
	s_cselect_b32 s44, s54, s55
	s_add_i32 s67, 0, 0x14000
	ds_read_b128 v[162:165], v151
	ds_read_b128 v[166:169], v151 offset:1024
	ds_read_b128 v[170:173], v151 offset:2048
	ds_read_b128 v[174:177], v151 offset:3072
	v_add_u32_e32 v151, s67, v141
	ds_read_b128 v[184:187], v151
	ds_read_b128 v[188:191], v151 offset:1024
	ds_read_b128 v[192:195], v151 offset:2048
	ds_read_b128 v[196:199], v151 offset:3072
	s_add_i32 m0, s25, 0xc000
	ds_read_b128 v[200:203], v149
	ds_read_b128 v[214:217], v149 offset:1024
	ds_read_b128 v[218:221], v149 offset:2048
	ds_read_b128 v[222:225], v149 offset:3072
	ds_read_b128 v[226:229], v149 offset:4096
	ds_read_b128 v[230:233], v149 offset:5120
	ds_read_b128 v[234:237], v149 offset:6144
	ds_read_b128 v[238:241], v149 offset:7168
	global_load_lds_dwordx4 v142, s[42:43]
	s_add_i32 m0, s25, 0xe000
	s_nop 0
	global_load_lds_dwordx4 v144, s[42:43]
	s_waitcnt vmcnt(8)
	s_waitcnt lgkmcnt(0)
	s_barrier
	s_setprio 1
	s_waitcnt lgkmcnt(0)
	v_mfma_f32_16x16x32_bf16 v[132:135], v[162:165], v[200:203], v[132:135]
	v_mfma_f32_16x16x32_bf16 v[128:131], v[170:173], v[200:203], v[128:131]
	v_mfma_f32_16x16x32_bf16 v[116:119], v[162:165], v[218:221], v[116:119]
	v_mfma_f32_16x16x32_bf16 v[112:115], v[170:173], v[218:221], v[112:115]
	v_mfma_f32_16x16x32_bf16 v[100:103], v[162:165], v[226:229], v[100:103]
	v_mfma_f32_16x16x32_bf16 v[96:99], v[170:173], v[226:229], v[96:99]
	v_mfma_f32_16x16x32_bf16 v[84:87], v[162:165], v[234:237], v[84:87]
	v_mfma_f32_16x16x32_bf16 v[80:83], v[170:173], v[234:237], v[80:83]
	v_mfma_f32_16x16x32_bf16 v[132:135], v[166:169], v[214:217], v[132:135]
	v_mfma_f32_16x16x32_bf16 v[128:131], v[174:177], v[214:217], v[128:131]
	v_mfma_f32_16x16x32_bf16 v[116:119], v[166:169], v[222:225], v[116:119]
	v_mfma_f32_16x16x32_bf16 v[112:115], v[174:177], v[222:225], v[112:115]
	v_mfma_f32_16x16x32_bf16 v[100:103], v[166:169], v[230:233], v[100:103]
	v_mfma_f32_16x16x32_bf16 v[96:99], v[174:177], v[230:233], v[96:99]
	v_mfma_f32_16x16x32_bf16 v[84:87], v[166:169], v[238:241], v[84:87]
	v_mfma_f32_16x16x32_bf16 v[80:83], v[174:177], v[238:241], v[80:83]
	s_setprio 0
	s_setprio 1
	v_mfma_f32_16x16x32_bf16 v[124:127], v[184:187], v[200:203], v[124:127]
	v_mfma_f32_16x16x32_bf16 v[120:123], v[192:195], v[200:203], v[120:123]
	v_mfma_f32_16x16x32_bf16 v[108:111], v[184:187], v[218:221], v[108:111]
	v_mfma_f32_16x16x32_bf16 v[104:107], v[192:195], v[218:221], v[104:107]
	v_mfma_f32_16x16x32_bf16 v[92:95], v[184:187], v[226:229], v[92:95]
	v_mfma_f32_16x16x32_bf16 v[88:91], v[192:195], v[226:229], v[88:91]
	v_mfma_f32_16x16x32_bf16 v[76:79], v[184:187], v[234:237], v[76:79]
	v_mfma_f32_16x16x32_bf16 v[72:75], v[192:195], v[234:237], v[72:75]
	v_mfma_f32_16x16x32_bf16 v[124:127], v[188:191], v[214:217], v[124:127]
	v_mfma_f32_16x16x32_bf16 v[120:123], v[196:199], v[214:217], v[120:123]
	v_mfma_f32_16x16x32_bf16 v[108:111], v[188:191], v[222:225], v[108:111]
	v_mfma_f32_16x16x32_bf16 v[104:107], v[196:199], v[222:225], v[104:107]
	v_mfma_f32_16x16x32_bf16 v[92:95], v[188:191], v[230:233], v[92:95]
	v_mfma_f32_16x16x32_bf16 v[88:91], v[196:199], v[230:233], v[88:91]
	v_mfma_f32_16x16x32_bf16 v[76:79], v[188:191], v[238:241], v[76:79]
	v_mfma_f32_16x16x32_bf16 v[72:75], v[196:199], v[238:241], v[72:75]
	s_setprio 0
	s_barrier
	s_add_u32 s98, s44, s22
	s_addc_u32 s99, s45, s23
	s_add_u32 s100, s46, s22
	s_addc_u32 s101, s47, s23
	s_add_i32 s64, s64, s20
	s_mov_b32 m0, s64
	ds_read_b128 v[200:203], v149 offset:16384
	ds_read_b128 v[214:217], v149 offset:17408
	ds_read_b128 v[218:221], v149 offset:18432
	ds_read_b128 v[222:225], v149 offset:19456
	ds_read_b128 v[226:229], v149 offset:20480
	ds_read_b128 v[230:233], v149 offset:21504
	ds_read_b128 v[234:237], v149 offset:22528
	ds_read_b128 v[238:241], v149 offset:23552
	global_load_lds_dwordx4 v34, s[44:45]
	s_add_i32 m0, s64, 0x2000
	s_add_u32 s64, s44, 0x80000
	s_addc_u32 s65, s45, 0
	s_add_i32 s67, s67, s20
	global_load_lds_dwordx4 v14, s[44:45]
	s_mov_b32 m0, s67
	s_nop 0
	global_load_lds_dwordx4 v34, s[64:65]
	s_add_i32 m0, s67, 0x2000
	s_nop 0
	global_load_lds_dwordx4 v14, s[64:65]
	s_mov_b32 m0, s25
	s_nop 0
	global_load_lds_dwordx4 v138, s[46:47]
	s_mov_b32 m0, s26
	s_nop 0
	global_load_lds_dwordx4 v136, s[46:47]
	s_waitcnt vmcnt(8)
	s_waitcnt lgkmcnt(0)
	s_barrier
	s_setprio 1
	s_waitcnt lgkmcnt(0)
	v_mfma_f32_16x16x32_bf16 v[68:71], v[162:165], v[200:203], v[68:71]
	v_mfma_f32_16x16x32_bf16 v[64:67], v[170:173], v[200:203], v[64:67]
	v_mfma_f32_16x16x32_bf16 v[52:55], v[162:165], v[218:221], v[52:55]
	v_mfma_f32_16x16x32_bf16 v[48:51], v[170:173], v[218:221], v[48:51]
	v_mfma_f32_16x16x32_bf16 v[36:39], v[162:165], v[226:229], v[36:39]
	v_mfma_f32_16x16x32_bf16 v[30:33], v[170:173], v[226:229], v[30:33]
	v_mfma_f32_16x16x32_bf16 v[18:21], v[162:165], v[234:237], v[18:21]
	v_mfma_f32_16x16x32_bf16 v[10:13], v[170:173], v[234:237], v[10:13]
	v_mfma_f32_16x16x32_bf16 v[68:71], v[166:169], v[214:217], v[68:71]
	v_mfma_f32_16x16x32_bf16 v[64:67], v[174:177], v[214:217], v[64:67]
	v_mfma_f32_16x16x32_bf16 v[52:55], v[166:169], v[222:225], v[52:55]
	v_mfma_f32_16x16x32_bf16 v[48:51], v[174:177], v[222:225], v[48:51]
	v_mfma_f32_16x16x32_bf16 v[36:39], v[166:169], v[230:233], v[36:39]
	v_mfma_f32_16x16x32_bf16 v[30:33], v[174:177], v[230:233], v[30:33]
	v_mfma_f32_16x16x32_bf16 v[18:21], v[166:169], v[238:241], v[18:21]
	v_mfma_f32_16x16x32_bf16 v[10:13], v[174:177], v[238:241], v[10:13]
	s_setprio 0
	s_setprio 1
	v_mfma_f32_16x16x32_bf16 v[60:63], v[184:187], v[200:203], v[60:63]
	v_mfma_f32_16x16x32_bf16 v[56:59], v[192:195], v[200:203], v[56:59]
	v_mfma_f32_16x16x32_bf16 v[44:47], v[184:187], v[218:221], v[44:47]
	v_mfma_f32_16x16x32_bf16 v[40:43], v[192:195], v[218:221], v[40:43]
	v_mfma_f32_16x16x32_bf16 v[26:29], v[184:187], v[226:229], v[26:29]
	v_mfma_f32_16x16x32_bf16 v[22:25], v[192:195], v[226:229], v[22:25]
	v_mfma_f32_16x16x32_bf16 v[6:9], v[184:187], v[234:237], v[6:9]
	v_mfma_f32_16x16x32_bf16 v[2:5], v[192:195], v[234:237], v[2:5]
	v_mfma_f32_16x16x32_bf16 v[60:63], v[188:191], v[214:217], v[60:63]
	v_mfma_f32_16x16x32_bf16 v[56:59], v[196:199], v[214:217], v[56:59]
	v_mfma_f32_16x16x32_bf16 v[44:47], v[188:191], v[222:225], v[44:47]
	v_mfma_f32_16x16x32_bf16 v[40:43], v[196:199], v[222:225], v[40:43]
	v_mfma_f32_16x16x32_bf16 v[26:29], v[188:191], v[230:233], v[26:29]
	v_mfma_f32_16x16x32_bf16 v[22:25], v[196:199], v[230:233], v[22:25]
	v_mfma_f32_16x16x32_bf16 v[6:9], v[188:191], v[238:241], v[6:9]
	v_mfma_f32_16x16x32_bf16 v[2:5], v[196:199], v[238:241], v[2:5]
	s_setprio 0
	s_barrier
	s_add_i32 s64, 0, 0x18000
	v_add_u32_e32 v151, s64, v141
	s_add_i32 s65, 0, 0x1c000
	ds_read_b128 v[162:165], v151
	ds_read_b128 v[166:169], v151 offset:1024
	ds_read_b128 v[170:173], v151 offset:2048
	ds_read_b128 v[174:177], v151 offset:3072
	v_add_u32_e32 v151, s65, v141
	ds_read_b128 v[184:187], v151
	ds_read_b128 v[188:191], v151 offset:1024
	ds_read_b128 v[192:195], v151 offset:2048
	ds_read_b128 v[196:199], v151 offset:3072
	s_add_u32 s46, s46, 0x80000
	s_addc_u32 s47, s47, 0
	s_mov_b32 m0, s27
	ds_read_b128 v[200:203], v149 offset:32768
	ds_read_b128 v[214:217], v149 offset:33792
	ds_read_b128 v[218:221], v149 offset:34816
	ds_read_b128 v[222:225], v149 offset:35840
	ds_read_b128 v[226:229], v149 offset:36864
	ds_read_b128 v[230:233], v149 offset:37888
	ds_read_b128 v[234:237], v149 offset:38912
	ds_read_b128 v[238:241], v149 offset:39936
	global_load_lds_dwordx4 v138, s[46:47]
	s_mov_b32 m0, s31
	s_nop 0
	global_load_lds_dwordx4 v136, s[46:47]
	s_waitcnt vmcnt(8)
	s_waitcnt lgkmcnt(0)
	s_barrier
	s_setprio 1
	s_waitcnt lgkmcnt(0)
	v_mfma_f32_16x16x32_bf16 v[132:135], v[162:165], v[200:203], v[132:135]
	v_mfma_f32_16x16x32_bf16 v[128:131], v[170:173], v[200:203], v[128:131]
	v_mfma_f32_16x16x32_bf16 v[116:119], v[162:165], v[218:221], v[116:119]
	v_mfma_f32_16x16x32_bf16 v[112:115], v[170:173], v[218:221], v[112:115]
	v_mfma_f32_16x16x32_bf16 v[100:103], v[162:165], v[226:229], v[100:103]
	v_mfma_f32_16x16x32_bf16 v[96:99], v[170:173], v[226:229], v[96:99]
	v_mfma_f32_16x16x32_bf16 v[84:87], v[162:165], v[234:237], v[84:87]
	v_mfma_f32_16x16x32_bf16 v[80:83], v[170:173], v[234:237], v[80:83]
	v_mfma_f32_16x16x32_bf16 v[132:135], v[166:169], v[214:217], v[132:135]
	v_mfma_f32_16x16x32_bf16 v[128:131], v[174:177], v[214:217], v[128:131]
	v_mfma_f32_16x16x32_bf16 v[116:119], v[166:169], v[222:225], v[116:119]
	v_mfma_f32_16x16x32_bf16 v[112:115], v[174:177], v[222:225], v[112:115]
	v_mfma_f32_16x16x32_bf16 v[100:103], v[166:169], v[230:233], v[100:103]
	v_mfma_f32_16x16x32_bf16 v[96:99], v[174:177], v[230:233], v[96:99]
	v_mfma_f32_16x16x32_bf16 v[84:87], v[166:169], v[238:241], v[84:87]
	v_mfma_f32_16x16x32_bf16 v[80:83], v[174:177], v[238:241], v[80:83]
	s_setprio 0
	s_setprio 1
	v_mfma_f32_16x16x32_bf16 v[124:127], v[184:187], v[200:203], v[124:127]
	v_mfma_f32_16x16x32_bf16 v[120:123], v[192:195], v[200:203], v[120:123]
	v_mfma_f32_16x16x32_bf16 v[108:111], v[184:187], v[218:221], v[108:111]
	v_mfma_f32_16x16x32_bf16 v[104:107], v[192:195], v[218:221], v[104:107]
	v_mfma_f32_16x16x32_bf16 v[92:95], v[184:187], v[226:229], v[92:95]
	v_mfma_f32_16x16x32_bf16 v[88:91], v[192:195], v[226:229], v[88:91]
	v_mfma_f32_16x16x32_bf16 v[76:79], v[184:187], v[234:237], v[76:79]
	v_mfma_f32_16x16x32_bf16 v[72:75], v[192:195], v[234:237], v[72:75]
	v_mfma_f32_16x16x32_bf16 v[124:127], v[188:191], v[214:217], v[124:127]
	v_mfma_f32_16x16x32_bf16 v[120:123], v[196:199], v[214:217], v[120:123]
	v_mfma_f32_16x16x32_bf16 v[108:111], v[188:191], v[222:225], v[108:111]
	v_mfma_f32_16x16x32_bf16 v[104:107], v[196:199], v[222:225], v[104:107]
	v_mfma_f32_16x16x32_bf16 v[92:95], v[188:191], v[230:233], v[92:95]
	v_mfma_f32_16x16x32_bf16 v[88:91], v[196:199], v[230:233], v[88:91]
	v_mfma_f32_16x16x32_bf16 v[76:79], v[188:191], v[238:241], v[76:79]
	v_mfma_f32_16x16x32_bf16 v[72:75], v[196:199], v[238:241], v[72:75]
	s_setprio 0
	s_barrier
	s_add_i32 s46, s64, s20
	s_mov_b32 m0, s46
	ds_read_b128 v[200:203], v149 offset:49152
	ds_read_b128 v[214:217], v149 offset:50176
	ds_read_b128 v[218:221], v149 offset:51200
	ds_read_b128 v[222:225], v149 offset:52224
	ds_read_b128 v[226:229], v149 offset:53248
	ds_read_b128 v[230:233], v149 offset:54272
	ds_read_b128 v[234:237], v149 offset:55296
	ds_read_b128 v[238:241], v149 offset:56320
	global_load_lds_dwordx4 v34, s[98:99]
	s_add_i32 m0, s46, 0x2000
	s_add_u32 s44, s44, 0x80080
	s_addc_u32 s45, s45, 0
	s_add_i32 s46, s65, s20
	global_load_lds_dwordx4 v14, s[98:99]
	s_mov_b32 m0, s46
	s_nop 0
	global_load_lds_dwordx4 v34, s[44:45]
	s_add_i32 m0, s46, 0x2000
	s_nop 0
	global_load_lds_dwordx4 v14, s[44:45]
	s_mov_b32 m0, s48
	s_nop 0
	global_load_lds_dwordx4 v138, s[100:101]
	s_mov_b32 m0, s49
	s_nop 0
	global_load_lds_dwordx4 v136, s[100:101]
	s_waitcnt vmcnt(8)
	s_waitcnt lgkmcnt(0)
	s_barrier
	s_setprio 1
	s_waitcnt lgkmcnt(0)
	v_mfma_f32_16x16x32_bf16 v[68:71], v[162:165], v[200:203], v[68:71]
	v_mfma_f32_16x16x32_bf16 v[64:67], v[170:173], v[200:203], v[64:67]
	v_mfma_f32_16x16x32_bf16 v[52:55], v[162:165], v[218:221], v[52:55]
	v_mfma_f32_16x16x32_bf16 v[48:51], v[170:173], v[218:221], v[48:51]
	v_mfma_f32_16x16x32_bf16 v[36:39], v[162:165], v[226:229], v[36:39]
	v_mfma_f32_16x16x32_bf16 v[30:33], v[170:173], v[226:229], v[30:33]
	v_mfma_f32_16x16x32_bf16 v[18:21], v[162:165], v[234:237], v[18:21]
	v_mfma_f32_16x16x32_bf16 v[10:13], v[170:173], v[234:237], v[10:13]
	v_mfma_f32_16x16x32_bf16 v[68:71], v[166:169], v[214:217], v[68:71]
	v_mfma_f32_16x16x32_bf16 v[64:67], v[174:177], v[214:217], v[64:67]
	v_mfma_f32_16x16x32_bf16 v[52:55], v[166:169], v[222:225], v[52:55]
	v_mfma_f32_16x16x32_bf16 v[48:51], v[174:177], v[222:225], v[48:51]
	v_mfma_f32_16x16x32_bf16 v[36:39], v[166:169], v[230:233], v[36:39]
	v_mfma_f32_16x16x32_bf16 v[30:33], v[174:177], v[230:233], v[30:33]
	v_mfma_f32_16x16x32_bf16 v[18:21], v[166:169], v[238:241], v[18:21]
	v_mfma_f32_16x16x32_bf16 v[10:13], v[174:177], v[238:241], v[10:13]
	s_setprio 0
	s_setprio 1
	v_mfma_f32_16x16x32_bf16 v[60:63], v[184:187], v[200:203], v[60:63]
	v_mfma_f32_16x16x32_bf16 v[56:59], v[192:195], v[200:203], v[56:59]
	v_mfma_f32_16x16x32_bf16 v[44:47], v[184:187], v[218:221], v[44:47]
	v_mfma_f32_16x16x32_bf16 v[40:43], v[192:195], v[218:221], v[40:43]
	v_mfma_f32_16x16x32_bf16 v[26:29], v[184:187], v[226:229], v[26:29]
	v_mfma_f32_16x16x32_bf16 v[22:25], v[192:195], v[226:229], v[22:25]
	v_mfma_f32_16x16x32_bf16 v[6:9], v[184:187], v[234:237], v[6:9]
	v_mfma_f32_16x16x32_bf16 v[2:5], v[192:195], v[234:237], v[2:5]
	v_mfma_f32_16x16x32_bf16 v[60:63], v[188:191], v[214:217], v[60:63]
	v_mfma_f32_16x16x32_bf16 v[56:59], v[196:199], v[214:217], v[56:59]
	v_mfma_f32_16x16x32_bf16 v[44:47], v[188:191], v[222:225], v[44:47]
	v_mfma_f32_16x16x32_bf16 v[40:43], v[196:199], v[222:225], v[40:43]
	v_mfma_f32_16x16x32_bf16 v[26:29], v[188:191], v[230:233], v[26:29]
	v_mfma_f32_16x16x32_bf16 v[22:25], v[196:199], v[230:233], v[22:25]
	v_mfma_f32_16x16x32_bf16 v[6:9], v[188:191], v[238:241], v[6:9]
	v_mfma_f32_16x16x32_bf16 v[2:5], v[196:199], v[238:241], v[2:5]
	s_setprio 0
	s_barrier
	s_add_i32 s61, s61, 2
	s_add_u32 s42, s42, 0x100
	s_addc_u32 s43, s43, 0
	s_add_u32 s55, s55, 0x100
	s_addc_u32 s60, s60, 0
	s_cmp_gt_u32 s61, 29
	s_cbranch_scc0 .LBB0_1664
	s_and_b64 vcc, exec, s[10:11]
	s_cbranch_vccz .LBB0_1667
	s_barrier

.LBB0_1764:
	s_add_i32 vcc_lo, s44, 2
	s_add_u32 s42, s36, 0x100
	s_addc_u32 s43, s37, 0
	s_add_i32 s72, 0, 0x10000
	s_cmp_eq_u32 s11, s44
	s_cselect_b32 s47, s13, s43
	s_cselect_b32 s46, s12, s42
	s_cselect_b32 s45, s29, s71
	s_cselect_b32 s44, s28, s70
	s_add_i32 s73, 0, 0x14000
	v_add_u32_e32 v160, s72, v152
	v_add_u32_e32 v176, s73, v152
	ds_read_b128 v[136:139], v160
	ds_read_b128 v[148:151], v160 offset:1024
	ds_read_b128 v[156:159], v160 offset:2048
	ds_read_b128 v[160:163], v160 offset:3072
	ds_read_b128 v[164:167], v176
	ds_read_b128 v[168:171], v176 offset:1024
	ds_read_b128 v[172:175], v176 offset:2048
	ds_read_b128 v[184:187], v176 offset:3072
	s_add_i32 m0, s25, 0xc000
	ds_read_b128 v[188:191], v155
	ds_read_b128 v[192:195], v155 offset:1024
	ds_read_b128 v[196:199], v155 offset:2048
	ds_read_b128 v[200:203], v155 offset:3072
	ds_read_b128 v[214:217], v155 offset:4096
	ds_read_b128 v[218:221], v155 offset:5120
	ds_read_b128 v[222:225], v155 offset:6144
	ds_read_b128 v[226:229], v155 offset:7168
	global_load_lds_dwordx4 v144, s[36:37]
	s_add_i32 m0, s25, 0xe000
	s_nop 0
	global_load_lds_dwordx4 v146, s[36:37]
	s_waitcnt vmcnt(8)
	s_waitcnt lgkmcnt(0)
	s_barrier
	s_setprio 1
	s_waitcnt lgkmcnt(0)
	v_mfma_f32_16x16x32_bf16 v[132:135], v[136:139], v[188:191], v[132:135]
	v_mfma_f32_16x16x32_bf16 v[128:131], v[156:159], v[188:191], v[128:131]
	v_mfma_f32_16x16x32_bf16 v[116:119], v[136:139], v[196:199], v[116:119]
	v_mfma_f32_16x16x32_bf16 v[112:115], v[156:159], v[196:199], v[112:115]
	v_mfma_f32_16x16x32_bf16 v[100:103], v[136:139], v[214:217], v[100:103]
	v_mfma_f32_16x16x32_bf16 v[96:99], v[156:159], v[214:217], v[96:99]
	v_mfma_f32_16x16x32_bf16 v[84:87], v[136:139], v[222:225], v[84:87]
	v_mfma_f32_16x16x32_bf16 v[80:83], v[156:159], v[222:225], v[80:83]
	v_mfma_f32_16x16x32_bf16 v[132:135], v[148:151], v[192:195], v[132:135]
	v_mfma_f32_16x16x32_bf16 v[128:131], v[160:163], v[192:195], v[128:131]
	v_mfma_f32_16x16x32_bf16 v[116:119], v[148:151], v[200:203], v[116:119]
	v_mfma_f32_16x16x32_bf16 v[112:115], v[160:163], v[200:203], v[112:115]
	v_mfma_f32_16x16x32_bf16 v[100:103], v[148:151], v[218:221], v[100:103]
	v_mfma_f32_16x16x32_bf16 v[96:99], v[160:163], v[218:221], v[96:99]
	v_mfma_f32_16x16x32_bf16 v[84:87], v[148:151], v[226:229], v[84:87]
	v_mfma_f32_16x16x32_bf16 v[80:83], v[160:163], v[226:229], v[80:83]
	s_setprio 0
	s_setprio 1
	v_mfma_f32_16x16x32_bf16 v[124:127], v[164:167], v[188:191], v[124:127]
	v_mfma_f32_16x16x32_bf16 v[120:123], v[172:175], v[188:191], v[120:123]
	v_mfma_f32_16x16x32_bf16 v[108:111], v[164:167], v[196:199], v[108:111]
	v_mfma_f32_16x16x32_bf16 v[104:107], v[172:175], v[196:199], v[104:107]
	v_mfma_f32_16x16x32_bf16 v[92:95], v[164:167], v[214:217], v[92:95]
	v_mfma_f32_16x16x32_bf16 v[88:91], v[172:175], v[214:217], v[88:91]
	v_mfma_f32_16x16x32_bf16 v[76:79], v[164:167], v[222:225], v[76:79]
	v_mfma_f32_16x16x32_bf16 v[72:75], v[172:175], v[222:225], v[72:75]
	v_mfma_f32_16x16x32_bf16 v[124:127], v[168:171], v[192:195], v[124:127]
	v_mfma_f32_16x16x32_bf16 v[120:123], v[184:187], v[192:195], v[120:123]
	v_mfma_f32_16x16x32_bf16 v[108:111], v[168:171], v[200:203], v[108:111]
	v_mfma_f32_16x16x32_bf16 v[104:107], v[184:187], v[200:203], v[104:107]
	v_mfma_f32_16x16x32_bf16 v[92:95], v[168:171], v[218:221], v[92:95]
	v_mfma_f32_16x16x32_bf16 v[88:91], v[184:187], v[218:221], v[88:91]
	v_mfma_f32_16x16x32_bf16 v[76:79], v[168:171], v[226:229], v[76:79]
	v_mfma_f32_16x16x32_bf16 v[72:75], v[184:187], v[226:229], v[72:75]
	s_setprio 0
	s_barrier
	s_add_u32 s98, s44, s22
	s_addc_u32 s99, s45, s23
	s_add_u32 s100, s46, s22
	s_addc_u32 s101, s47, s23
	s_add_i32 s36, s72, s20
	s_mov_b32 m0, s36
	ds_read_b128 v[188:191], v155 offset:16384
	ds_read_b128 v[192:195], v155 offset:17408
	ds_read_b128 v[196:199], v155 offset:18432
	ds_read_b128 v[200:203], v155 offset:19456
	ds_read_b128 v[214:217], v155 offset:20480
	ds_read_b128 v[218:221], v155 offset:21504
	ds_read_b128 v[222:225], v155 offset:22528
	ds_read_b128 v[226:229], v155 offset:23552
	global_load_lds_dwordx4 v34, s[44:45]
	s_add_i32 m0, s36, 0x2000
	s_add_u32 s36, s44, 0x160000
	s_addc_u32 s37, s45, 0
	s_add_i32 s72, s73, s20
	global_load_lds_dwordx4 v142, s[44:45]
	s_mov_b32 m0, s72
	s_nop 0
	global_load_lds_dwordx4 v34, s[36:37]
	s_add_i32 m0, s72, 0x2000
	s_nop 0
	global_load_lds_dwordx4 v142, s[36:37]
	s_mov_b32 m0, s25
	s_nop 0
	global_load_lds_dwordx4 v14, s[46:47]
	s_mov_b32 m0, s26
	s_nop 0
	global_load_lds_dwordx4 v140, s[46:47]
	s_waitcnt vmcnt(8)
	s_waitcnt lgkmcnt(0)
	s_barrier
	s_setprio 1
	s_waitcnt lgkmcnt(0)
	v_mfma_f32_16x16x32_bf16 v[68:71], v[136:139], v[188:191], v[68:71]
	v_mfma_f32_16x16x32_bf16 v[64:67], v[156:159], v[188:191], v[64:67]
	v_mfma_f32_16x16x32_bf16 v[52:55], v[136:139], v[196:199], v[52:55]
	v_mfma_f32_16x16x32_bf16 v[48:51], v[156:159], v[196:199], v[48:51]
	v_mfma_f32_16x16x32_bf16 v[36:39], v[136:139], v[214:217], v[36:39]
	v_mfma_f32_16x16x32_bf16 v[30:33], v[156:159], v[214:217], v[30:33]
	v_mfma_f32_16x16x32_bf16 v[18:21], v[136:139], v[222:225], v[18:21]
	v_mfma_f32_16x16x32_bf16 v[10:13], v[156:159], v[222:225], v[10:13]
	v_mfma_f32_16x16x32_bf16 v[68:71], v[148:151], v[192:195], v[68:71]
	v_mfma_f32_16x16x32_bf16 v[64:67], v[160:163], v[192:195], v[64:67]
	v_mfma_f32_16x16x32_bf16 v[52:55], v[148:151], v[200:203], v[52:55]
	v_mfma_f32_16x16x32_bf16 v[48:51], v[160:163], v[200:203], v[48:51]
	v_mfma_f32_16x16x32_bf16 v[36:39], v[148:151], v[218:221], v[36:39]
	v_mfma_f32_16x16x32_bf16 v[30:33], v[160:163], v[218:221], v[30:33]
	v_mfma_f32_16x16x32_bf16 v[18:21], v[148:151], v[226:229], v[18:21]
	v_mfma_f32_16x16x32_bf16 v[10:13], v[160:163], v[226:229], v[10:13]
	s_setprio 0
	s_setprio 1
	v_mfma_f32_16x16x32_bf16 v[60:63], v[164:167], v[188:191], v[60:63]
	v_mfma_f32_16x16x32_bf16 v[56:59], v[172:175], v[188:191], v[56:59]
	v_mfma_f32_16x16x32_bf16 v[44:47], v[164:167], v[196:199], v[44:47]
	v_mfma_f32_16x16x32_bf16 v[40:43], v[172:175], v[196:199], v[40:43]
	v_mfma_f32_16x16x32_bf16 v[26:29], v[164:167], v[214:217], v[26:29]
	v_mfma_f32_16x16x32_bf16 v[22:25], v[172:175], v[214:217], v[22:25]
	v_mfma_f32_16x16x32_bf16 v[6:9], v[164:167], v[222:225], v[6:9]
	v_mfma_f32_16x16x32_bf16 v[2:5], v[172:175], v[222:225], v[2:5]
	v_mfma_f32_16x16x32_bf16 v[60:63], v[168:171], v[192:195], v[60:63]
	v_mfma_f32_16x16x32_bf16 v[56:59], v[184:187], v[192:195], v[56:59]
	v_mfma_f32_16x16x32_bf16 v[44:47], v[168:171], v[200:203], v[44:47]
	v_mfma_f32_16x16x32_bf16 v[40:43], v[184:187], v[200:203], v[40:43]
	v_mfma_f32_16x16x32_bf16 v[26:29], v[168:171], v[218:221], v[26:29]
	v_mfma_f32_16x16x32_bf16 v[22:25], v[184:187], v[218:221], v[22:25]
	v_mfma_f32_16x16x32_bf16 v[6:9], v[168:171], v[226:229], v[6:9]
	v_mfma_f32_16x16x32_bf16 v[2:5], v[184:187], v[226:229], v[2:5]
	s_setprio 0
	s_barrier
	s_add_i32 s72, 0, 0x18000
	s_add_i32 s73, 0, 0x1c000
	v_add_u32_e32 v160, s72, v152
	v_add_u32_e32 v183, s73, v152
	ds_read_b128 v[136:139], v160
	ds_read_b128 v[148:151], v160 offset:1024
	ds_read_b128 v[156:159], v160 offset:2048
	ds_read_b128 v[160:163], v160 offset:3072
	ds_read_b128 v[164:167], v183
	ds_read_b128 v[168:171], v183 offset:1024
	ds_read_b128 v[172:175], v183 offset:2048
	ds_read_b128 v[184:187], v183 offset:3072
	s_add_u32 s36, s46, 0x160000
	s_addc_u32 s37, s47, 0
	s_mov_b32 m0, s27
	ds_read_b128 v[188:191], v155 offset:32768
	ds_read_b128 v[192:195], v155 offset:33792
	ds_read_b128 v[196:199], v155 offset:34816
	ds_read_b128 v[200:203], v155 offset:35840
	ds_read_b128 v[214:217], v155 offset:36864
	ds_read_b128 v[218:221], v155 offset:37888
	ds_read_b128 v[222:225], v155 offset:38912
	ds_read_b128 v[226:229], v155 offset:39936
	global_load_lds_dwordx4 v14, s[36:37]
	s_mov_b32 m0, s31
	s_nop 0
	global_load_lds_dwordx4 v140, s[36:37]
	s_waitcnt vmcnt(8)
	s_waitcnt lgkmcnt(0)
	s_barrier
	s_setprio 1
	s_waitcnt lgkmcnt(0)
	v_mfma_f32_16x16x32_bf16 v[132:135], v[136:139], v[188:191], v[132:135]
	v_mfma_f32_16x16x32_bf16 v[128:131], v[156:159], v[188:191], v[128:131]
	v_mfma_f32_16x16x32_bf16 v[116:119], v[136:139], v[196:199], v[116:119]
	v_mfma_f32_16x16x32_bf16 v[112:115], v[156:159], v[196:199], v[112:115]
	v_mfma_f32_16x16x32_bf16 v[100:103], v[136:139], v[214:217], v[100:103]
	v_mfma_f32_16x16x32_bf16 v[96:99], v[156:159], v[214:217], v[96:99]
	v_mfma_f32_16x16x32_bf16 v[84:87], v[136:139], v[222:225], v[84:87]
	v_mfma_f32_16x16x32_bf16 v[80:83], v[156:159], v[222:225], v[80:83]
	v_mfma_f32_16x16x32_bf16 v[132:135], v[148:151], v[192:195], v[132:135]
	v_mfma_f32_16x16x32_bf16 v[128:131], v[160:163], v[192:195], v[128:131]
	v_mfma_f32_16x16x32_bf16 v[116:119], v[148:151], v[200:203], v[116:119]
	v_mfma_f32_16x16x32_bf16 v[112:115], v[160:163], v[200:203], v[112:115]
	v_mfma_f32_16x16x32_bf16 v[100:103], v[148:151], v[218:221], v[100:103]
	v_mfma_f32_16x16x32_bf16 v[96:99], v[160:163], v[218:221], v[96:99]
	v_mfma_f32_16x16x32_bf16 v[84:87], v[148:151], v[226:229], v[84:87]
	v_mfma_f32_16x16x32_bf16 v[80:83], v[160:163], v[226:229], v[80:83]
	s_setprio 0
	s_setprio 1
	v_mfma_f32_16x16x32_bf16 v[124:127], v[164:167], v[188:191], v[124:127]
	v_mfma_f32_16x16x32_bf16 v[120:123], v[172:175], v[188:191], v[120:123]
	v_mfma_f32_16x16x32_bf16 v[108:111], v[164:167], v[196:199], v[108:111]
	v_mfma_f32_16x16x32_bf16 v[104:107], v[172:175], v[196:199], v[104:107]
	v_mfma_f32_16x16x32_bf16 v[92:95], v[164:167], v[214:217], v[92:95]
	v_mfma_f32_16x16x32_bf16 v[88:91], v[172:175], v[214:217], v[88:91]
	v_mfma_f32_16x16x32_bf16 v[76:79], v[164:167], v[222:225], v[76:79]
	v_mfma_f32_16x16x32_bf16 v[72:75], v[172:175], v[222:225], v[72:75]
	v_mfma_f32_16x16x32_bf16 v[124:127], v[168:171], v[192:195], v[124:127]
	v_mfma_f32_16x16x32_bf16 v[120:123], v[184:187], v[192:195], v[120:123]
	v_mfma_f32_16x16x32_bf16 v[108:111], v[168:171], v[200:203], v[108:111]
	v_mfma_f32_16x16x32_bf16 v[104:107], v[184:187], v[200:203], v[104:107]
	v_mfma_f32_16x16x32_bf16 v[92:95], v[168:171], v[218:221], v[92:95]
	v_mfma_f32_16x16x32_bf16 v[88:91], v[184:187], v[218:221], v[88:91]
	v_mfma_f32_16x16x32_bf16 v[76:79], v[168:171], v[226:229], v[76:79]
	v_mfma_f32_16x16x32_bf16 v[72:75], v[184:187], v[226:229], v[72:75]
	s_setprio 0
	s_barrier
	s_add_i32 s36, s72, s20
	s_mov_b32 m0, s36
	ds_read_b128 v[188:191], v155 offset:49152
	ds_read_b128 v[192:195], v155 offset:50176
	ds_read_b128 v[196:199], v155 offset:51200
	ds_read_b128 v[200:203], v155 offset:52224
	ds_read_b128 v[214:217], v155 offset:53248
	ds_read_b128 v[218:221], v155 offset:54272
	ds_read_b128 v[222:225], v155 offset:55296
	ds_read_b128 v[226:229], v155 offset:56320
	global_load_lds_dwordx4 v34, s[98:99]
	s_add_i32 m0, s36, 0x2000
	s_add_u32 s36, s44, 0x160080
	s_addc_u32 s37, s45, 0
	s_add_i32 s44, s73, s20
	global_load_lds_dwordx4 v142, s[98:99]
	s_mov_b32 m0, s44
	s_nop 0
	global_load_lds_dwordx4 v34, s[36:37]
	s_add_i32 m0, s44, 0x2000
	s_nop 0
	global_load_lds_dwordx4 v142, s[36:37]
	s_mov_b32 m0, s50
	s_nop 0
	global_load_lds_dwordx4 v14, s[100:101]
	s_mov_b32 m0, s51
	s_nop 0
	global_load_lds_dwordx4 v140, s[100:101]
	s_waitcnt vmcnt(8)
	s_waitcnt lgkmcnt(0)
	s_barrier
	s_setprio 1
	s_waitcnt lgkmcnt(0)
	v_mfma_f32_16x16x32_bf16 v[68:71], v[136:139], v[188:191], v[68:71]
	v_mfma_f32_16x16x32_bf16 v[64:67], v[156:159], v[188:191], v[64:67]
	v_mfma_f32_16x16x32_bf16 v[52:55], v[136:139], v[196:199], v[52:55]
	v_mfma_f32_16x16x32_bf16 v[48:51], v[156:159], v[196:199], v[48:51]
	v_mfma_f32_16x16x32_bf16 v[36:39], v[136:139], v[214:217], v[36:39]
	v_mfma_f32_16x16x32_bf16 v[30:33], v[156:159], v[214:217], v[30:33]
	v_mfma_f32_16x16x32_bf16 v[18:21], v[136:139], v[222:225], v[18:21]
	v_mfma_f32_16x16x32_bf16 v[10:13], v[156:159], v[222:225], v[10:13]
	v_mfma_f32_16x16x32_bf16 v[68:71], v[148:151], v[192:195], v[68:71]
	v_mfma_f32_16x16x32_bf16 v[64:67], v[160:163], v[192:195], v[64:67]
	v_mfma_f32_16x16x32_bf16 v[52:55], v[148:151], v[200:203], v[52:55]
	v_mfma_f32_16x16x32_bf16 v[48:51], v[160:163], v[200:203], v[48:51]
	v_mfma_f32_16x16x32_bf16 v[36:39], v[148:151], v[218:221], v[36:39]
	v_mfma_f32_16x16x32_bf16 v[30:33], v[160:163], v[218:221], v[30:33]
	v_mfma_f32_16x16x32_bf16 v[18:21], v[148:151], v[226:229], v[18:21]
	v_mfma_f32_16x16x32_bf16 v[10:13], v[160:163], v[226:229], v[10:13]
	s_setprio 0
	s_setprio 1
	v_mfma_f32_16x16x32_bf16 v[60:63], v[164:167], v[188:191], v[60:63]
	v_mfma_f32_16x16x32_bf16 v[56:59], v[172:175], v[188:191], v[56:59]
	v_mfma_f32_16x16x32_bf16 v[44:47], v[164:167], v[196:199], v[44:47]
	v_mfma_f32_16x16x32_bf16 v[40:43], v[172:175], v[196:199], v[40:43]
	v_mfma_f32_16x16x32_bf16 v[26:29], v[164:167], v[214:217], v[26:29]
	v_mfma_f32_16x16x32_bf16 v[22:25], v[172:175], v[214:217], v[22:25]
	v_mfma_f32_16x16x32_bf16 v[6:9], v[164:167], v[222:225], v[6:9]
	v_mfma_f32_16x16x32_bf16 v[2:5], v[172:175], v[222:225], v[2:5]
	v_mfma_f32_16x16x32_bf16 v[60:63], v[168:171], v[192:195], v[60:63]
	v_mfma_f32_16x16x32_bf16 v[56:59], v[184:187], v[192:195], v[56:59]
	v_mfma_f32_16x16x32_bf16 v[44:47], v[168:171], v[200:203], v[44:47]
	v_mfma_f32_16x16x32_bf16 v[40:43], v[184:187], v[200:203], v[40:43]
	v_mfma_f32_16x16x32_bf16 v[26:29], v[168:171], v[218:221], v[26:29]
	v_mfma_f32_16x16x32_bf16 v[22:25], v[184:187], v[218:221], v[22:25]
	v_mfma_f32_16x16x32_bf16 v[6:9], v[168:171], v[226:229], v[6:9]
	v_mfma_f32_16x16x32_bf16 v[2:5], v[184:187], v[226:229], v[2:5]
	s_setprio 0
	s_barrier
	s_add_u32 s70, s70, 0x100
	s_addc_u32 s71, s71, 0
	s_cmp_ge_i32 vcc_lo, s67
	s_mov_b64 s[36:37], s[42:43]
	s_mov_b32 s44, vcc_lo
	s_cbranch_scc0 .LBB0_1764
	s_mov_b32 s71, 0x200000
	s_and_b64 vcc, exec, s[8:9]
	s_cbranch_vccz .LBB0_1767
